# fp6 GEMM main loops: one static s_setprio 1 per unit for the wave half that runs a segment behind (waves 4-7), reset after the loop
# speedup vs baseline: 1.0091x; 1.0091x over previous
.LBB0_990:
	s_ashr_i32 s45, s44, 31
	s_lshl_b64 s[4:5], s[44:45], 19
	s_add_u32 s46, s0, s4
	s_addc_u32 s47, s1, s5
	s_and_b64 s[4:5], s[6:7], exec
	s_cselect_b32 s4, s47, s55
	s_cselect_b32 s5, s46, s54
	s_ashr_i32 s39, s38, 31
	s_lshl_b64 s[48:49], s[38:39], 19
	s_add_u32 s48, s2, s48
	s_addc_u32 s49, s3, s49
	s_and_b64 s[58:59], s[6:7], exec
	s_cselect_b32 s39, s49, s57
	s_cselect_b32 s45, s48, s56
	s_add_u32 s54, s54, 0x40080
	s_addc_u32 s55, s55, 0
	s_add_u32 s84, s56, 0x100
	v_mov_b32_e32 v36, 0
	s_addc_u32 s85, s57, 0
	s_mov_b32 s86, -2
	v_mov_b32_e32 v37, v36
	v_mov_b32_e32 v38, v36
	v_mov_b32_e32 v39, v36
	v_mov_b32_e32 v40, v36
	v_mov_b32_e32 v41, v36
	v_mov_b32_e32 v42, v36
	v_mov_b32_e32 v43, v36
	v_mov_b32_e32 v48, v36
	v_mov_b32_e32 v49, v36
	v_mov_b32_e32 v50, v36
	v_mov_b32_e32 v51, v36
	v_mov_b32_e32 v60, v36
	v_mov_b32_e32 v61, v36
	v_mov_b32_e32 v62, v36
	v_mov_b32_e32 v63, v36
	v_mov_b32_e32 v64, v36
	v_mov_b32_e32 v65, v36
	v_mov_b32_e32 v66, v36
	v_mov_b32_e32 v67, v36
	v_mov_b32_e32 v72, v36
	v_mov_b32_e32 v73, v36
	v_mov_b32_e32 v74, v36
	v_mov_b32_e32 v75, v36
	v_mov_b32_e32 v84, v36
	v_mov_b32_e32 v85, v36
	v_mov_b32_e32 v86, v36
	v_mov_b32_e32 v87, v36
	v_mov_b32_e32 v88, v36
	v_mov_b32_e32 v89, v36
	v_mov_b32_e32 v90, v36
	v_mov_b32_e32 v91, v36
	v_mov_b32_e32 v44, v36
	v_mov_b32_e32 v45, v36
	v_mov_b32_e32 v46, v36
	v_mov_b32_e32 v47, v36
	v_mov_b32_e32 v52, v36
	v_mov_b32_e32 v53, v36
	v_mov_b32_e32 v54, v36
	v_mov_b32_e32 v55, v36
	v_mov_b32_e32 v56, v36
	v_mov_b32_e32 v57, v36
	v_mov_b32_e32 v58, v36
	v_mov_b32_e32 v59, v36
	v_mov_b32_e32 v68, v36
	v_mov_b32_e32 v69, v36
	v_mov_b32_e32 v70, v36
	v_mov_b32_e32 v71, v36
	v_mov_b32_e32 v76, v36
	v_mov_b32_e32 v77, v36
	v_mov_b32_e32 v78, v36
	v_mov_b32_e32 v79, v36
	v_mov_b32_e32 v80, v36
	v_mov_b32_e32 v81, v36
	v_mov_b32_e32 v82, v36
	v_mov_b32_e32 v83, v36
	v_mov_b32_e32 v92, v36
	v_mov_b32_e32 v93, v36
	v_mov_b32_e32 v94, v36
	v_mov_b32_e32 v95, v36
	v_mov_b32_e32 v96, v36
	v_mov_b32_e32 v97, v36
	v_mov_b32_e32 v98, v36
	v_mov_b32_e32 v99, v36
	v_mov_b32_e32 v30, v36
	v_mov_b32_e32 v31, v36
	v_mov_b32_e32 v32, v36
	v_mov_b32_e32 v33, v36
	v_mov_b32_e32 v26, v36
	v_mov_b32_e32 v27, v36
	v_mov_b32_e32 v28, v36
	v_mov_b32_e32 v29, v36
	v_mov_b32_e32 v22, v36
	v_mov_b32_e32 v23, v36
	v_mov_b32_e32 v24, v36
	v_mov_b32_e32 v25, v36
	v_mov_b32_e32 v18, v36
	v_mov_b32_e32 v19, v36
	v_mov_b32_e32 v20, v36
	v_mov_b32_e32 v21, v36
	v_mov_b32_e32 v14, v36
	v_mov_b32_e32 v15, v36
	v_mov_b32_e32 v16, v36
	v_mov_b32_e32 v17, v36
	v_mov_b32_e32 v10, v36
	v_mov_b32_e32 v11, v36
	v_mov_b32_e32 v12, v36
	v_mov_b32_e32 v13, v36
	v_mov_b32_e32 v6, v36
	v_mov_b32_e32 v7, v36
	v_mov_b32_e32 v8, v36
	v_mov_b32_e32 v9, v36
	v_mov_b32_e32 v2, v36
	v_mov_b32_e32 v3, v36
	v_mov_b32_e32 v4, v36
	v_mov_b32_e32 v5, v36
	v_mov_b32_e32 v100, v36
	v_mov_b32_e32 v101, v36
	v_mov_b32_e32 v102, v36
	v_mov_b32_e32 v103, v36
	v_mov_b32_e32 v104, v36
	v_mov_b32_e32 v105, v36
	v_mov_b32_e32 v106, v36
	v_mov_b32_e32 v107, v36
	v_mov_b32_e32 v108, v36
	v_mov_b32_e32 v109, v36
	v_mov_b32_e32 v110, v36
	v_mov_b32_e32 v111, v36
	v_mov_b32_e32 v112, v36
	v_mov_b32_e32 v113, v36
	v_mov_b32_e32 v114, v36
	v_mov_b32_e32 v115, v36
	v_mov_b32_e32 v116, v36
	v_mov_b32_e32 v117, v36
	v_mov_b32_e32 v118, v36
	v_mov_b32_e32 v119, v36
	v_mov_b32_e32 v120, v36
	v_mov_b32_e32 v121, v36
	v_mov_b32_e32 v122, v36
	v_mov_b32_e32 v123, v36
	v_mov_b32_e32 v124, v36
	v_mov_b32_e32 v125, v36
	v_mov_b32_e32 v126, v36
	v_mov_b32_e32 v127, v36
	v_mov_b32_e32 v128, v36
	v_mov_b32_e32 v129, v36
	v_mov_b32_e32 v130, v36
	v_mov_b32_e32 v131, v36
	v_readfirstlane_b32 s100, v0
	s_bitcmp1_b32 s100, 8
	s_cbranch_scc0 .Lfp6_prio_skip0
	s_setprio 1
.Lfp6_prio_skip0:
.LBB0_991:
	ds_read_b128 v[146:149], v142
	ds_read_b128 v[192:195], v142 offset:1024
	ds_read_b128 v[152:155], v142 offset:2048
	ds_read_b128 v[196:199], v142 offset:3072
	ds_read_b128 v[158:161], v143
	ds_read_b128 v[200:203], v143 offset:1024
	ds_read_b128 v[164:167], v143 offset:2048
	ds_read_b128 v[204:207], v143 offset:3072
	v_lshl_add_u64 v[150:151], s[54:55], 0, v[136:137]
	s_add_i32 m0, s29, 0xc000
	ds_read_b128 v[170:173], v144
	ds_read_b128 v[208:211], v144 offset:1024
	ds_read_b128 v[176:179], v144 offset:2048
	ds_read_b128 v[212:215], v144 offset:3072
	ds_read_b128 v[182:185], v144 offset:4096
	ds_read_b128 v[216:219], v144 offset:5120
	ds_read_b128 v[188:191], v144 offset:6144
	ds_read_b128 v[220:223], v144 offset:7168
	global_load_lds_dwordx4 v[150:151], off
	s_add_i32 m0, s29, 0xe000
	v_lshl_add_u64 v[150:151], v[150:151], 0, s[10:11]
	global_load_lds_dwordx4 v[150:151], off
	s_waitcnt vmcnt(8)
	s_waitcnt lgkmcnt(0)
	s_barrier
	s_waitcnt lgkmcnt(0)
	v_mov_b32_e32 v150, v192
	v_mov_b32_e32 v151, v193
	v_mov_b32_e32 v156, v196
	v_mov_b32_e32 v157, v197
	v_mov_b32_e32 v174, v208
	v_mov_b32_e32 v175, v209
	v_mov_b32_e32 v180, v212
	v_mov_b32_e32 v181, v213
	v_mov_b32_e32 v186, v216
	v_mov_b32_e32 v187, v217
	v_mov_b32_e32 v192, v220
	v_mov_b32_e32 v193, v221
	v_mfma_scale_f32_16x16x128_f8f6f4 v[128:131], v[146:151], v[170:175], v[128:131], v194, v210 op_sel_hi:[0,0,0] cbsz:2 blgp:2
	v_mfma_scale_f32_16x16x128_f8f6f4 v[124:127], v[152:157], v[170:175], v[124:127], v198, v210 op_sel_hi:[0,0,0] cbsz:2 blgp:2
	v_mfma_scale_f32_16x16x128_f8f6f4 v[120:123], v[146:151], v[176:181], v[120:123], v194, v214 op_sel_hi:[0,0,0] cbsz:2 blgp:2
	v_mfma_scale_f32_16x16x128_f8f6f4 v[116:119], v[152:157], v[176:181], v[116:119], v198, v214 op_sel_hi:[0,0,0] cbsz:2 blgp:2
	s_add_u32 s56, s54, 0xfffc0080
	s_addc_u32 s57, s55, -1
	s_cmp_eq_u32 s86, 12
	s_cselect_b32 s57, s4, s57
	s_cselect_b32 s56, s5, s56
	s_cselect_b32 s59, s39, s85
	s_cselect_b32 s58, s45, s84
	s_add_i32 s100, s61, s24
	s_add_i32 s101, s62, s24
	v_lshl_add_u64 v[236:237], s[58:59], 0, v[132:133]
	v_lshl_add_u64 v[238:239], s[56:57], 0, v[134:135]
	v_lshl_add_u64 v[240:241], v[236:237], 0, s[10:11]
	v_lshl_add_u64 v[242:243], v[236:237], 0, s[12:13]
	v_lshl_add_u64 v[244:245], v[236:237], 0, s[14:15]
	v_lshl_add_u64 v[246:247], v[238:239], 0, s[10:11]
	v_mfma_scale_f32_16x16x128_f8f6f4 v[112:115], v[146:151], v[182:187], v[112:115], v194, v218 op_sel_hi:[0,0,0] cbsz:2 blgp:2
	v_mfma_scale_f32_16x16x128_f8f6f4 v[108:111], v[152:157], v[182:187], v[108:111], v198, v218 op_sel_hi:[0,0,0] cbsz:2 blgp:2
	v_mfma_scale_f32_16x16x128_f8f6f4 v[104:107], v[146:151], v[188:193], v[104:107], v194, v222 op_sel_hi:[0,0,0] cbsz:2 blgp:2
	v_mfma_scale_f32_16x16x128_f8f6f4 v[100:103], v[152:157], v[188:193], v[100:103], v198, v222 op_sel_hi:[0,0,0] cbsz:2 blgp:2
	v_mov_b32_e32 v168, v204
	v_mov_b32_e32 v169, v205
	v_mov_b32_e32 v162, v200
	v_mov_b32_e32 v163, v201
	v_mfma_scale_f32_16x16x128_f8f6f4 v[30:33], v[164:169], v[188:193], v[30:33], v206, v222 op_sel_hi:[0,0,0] cbsz:2 blgp:2
	s_nop 0
	v_mfma_scale_f32_16x16x128_f8f6f4 v[224:227], v[158:163], v[170:175], v[2:5], v202, v210 op_sel_hi:[0,0,0] cbsz:2 blgp:2
	v_mfma_scale_f32_16x16x128_f8f6f4 v[170:173], v[164:169], v[170:175], v[6:9], v206, v210 op_sel_hi:[0,0,0] cbsz:2 blgp:2
	v_mfma_scale_f32_16x16x128_f8f6f4 v[208:211], v[158:163], v[176:181], v[10:13], v202, v214 op_sel_hi:[0,0,0] cbsz:2 blgp:2
	v_mfma_scale_f32_16x16x128_f8f6f4 v[174:177], v[164:169], v[176:181], v[14:17], v206, v214 op_sel_hi:[0,0,0] cbsz:2 blgp:2
	v_mfma_scale_f32_16x16x128_f8f6f4 v[178:181], v[158:163], v[182:187], v[18:21], v202, v218 op_sel_hi:[0,0,0] cbsz:2 blgp:2
	v_mfma_scale_f32_16x16x128_f8f6f4 v[182:185], v[164:169], v[182:187], v[22:25], v206, v218 op_sel_hi:[0,0,0] cbsz:2 blgp:2
	v_mfma_scale_f32_16x16x128_f8f6f4 v[212:215], v[158:163], v[188:193], v[26:29], v202, v222 op_sel_hi:[0,0,0] cbsz:2 blgp:2
	s_barrier
	s_mov_b32 m0, s100
	ds_read_b128 v[2:5], v144 offset:16384
	ds_read_b128 v[24:27], v144 offset:17408
	ds_read_b128 v[8:11], v144 offset:18432
	global_load_lds_dwordx4 v[236:237], off
	s_add_i32 m0, s100, 0x2000
	ds_read_b128 v[186:189], v144 offset:19456
	global_load_lds_dwordx4 v[240:241], off
	s_mov_b32 m0, s101
	ds_read_b128 v[14:17], v144 offset:20480
	global_load_lds_dwordx4 v[242:243], off
	s_add_i32 m0, s101, 0x2000
	ds_read_b128 v[190:193], v144 offset:21504
	global_load_lds_dwordx4 v[244:245], off
	s_mov_b32 m0, s29
	ds_read_b128 v[20:23], v144 offset:22528
	global_load_lds_dwordx4 v[238:239], off
	s_mov_b32 m0, s33
	ds_read_b128 v[216:219], v144 offset:23552
	global_load_lds_dwordx4 v[246:247], off
	s_waitcnt vmcnt(8)
	s_waitcnt lgkmcnt(0)
	s_barrier
	s_waitcnt lgkmcnt(0)
	v_mov_b32_e32 v6, v24
	v_mov_b32_e32 v7, v25
	v_mov_b32_e32 v12, v186
	v_mov_b32_e32 v13, v187
	v_mov_b32_e32 v18, v190
	v_mov_b32_e32 v19, v191
	v_mfma_scale_f32_16x16x128_f8f6f4 v[96:99], v[146:151], v[2:7], v[96:99], v194, v26 op_sel_hi:[0,0,0] cbsz:2 blgp:2
	v_mov_b32_e32 v24, v216
	v_mov_b32_e32 v25, v217
	v_mfma_scale_f32_16x16x128_f8f6f4 v[92:95], v[152:157], v[2:7], v[92:95], v198, v26 op_sel_hi:[0,0,0] cbsz:2 blgp:2
	v_mfma_scale_f32_16x16x128_f8f6f4 v[80:83], v[146:151], v[8:13], v[80:83], v194, v188 op_sel_hi:[0,0,0] cbsz:2 blgp:2
	v_mfma_scale_f32_16x16x128_f8f6f4 v[76:79], v[152:157], v[8:13], v[76:79], v198, v188 op_sel_hi:[0,0,0] cbsz:2 blgp:2
	s_add_i32 s56, 0, 0x18000
	s_add_i32 s57, 0, 0x1c000
	v_add_u32_e32 v252, 0x18000, v1
	v_add_u32_e32 v253, 0x1c000, v1
	v_lshl_add_u64 v[248:249], v[238:239], 0, s[12:13]
	v_lshl_add_u64 v[250:251], v[238:239], 0, s[14:15]
	v_mfma_scale_f32_16x16x128_f8f6f4 v[68:71], v[146:151], v[14:19], v[68:71], v194, v192 op_sel_hi:[0,0,0] cbsz:2 blgp:2
	v_mfma_scale_f32_16x16x128_f8f6f4 v[56:59], v[152:157], v[14:19], v[56:59], v198, v192 op_sel_hi:[0,0,0] cbsz:2 blgp:2
	v_mfma_scale_f32_16x16x128_f8f6f4 v[194:197], v[146:151], v[20:25], v[52:55], v194, v218 op_sel_hi:[0,0,0] cbsz:2 blgp:2
	v_mfma_scale_f32_16x16x128_f8f6f4 v[198:201], v[152:157], v[20:25], v[44:47], v198, v218 op_sel_hi:[0,0,0] cbsz:2 blgp:2
	v_mfma_scale_f32_16x16x128_f8f6f4 v[88:91], v[158:163], v[2:7], v[88:91], v202, v26 op_sel_hi:[0,0,0] cbsz:2 blgp:2
	v_mfma_scale_f32_16x16x128_f8f6f4 v[84:87], v[164:169], v[2:7], v[84:87], v206, v26 op_sel_hi:[0,0,0] cbsz:2 blgp:2
	v_mfma_scale_f32_16x16x128_f8f6f4 v[72:75], v[158:163], v[8:13], v[72:75], v202, v188 op_sel_hi:[0,0,0] cbsz:2 blgp:2
	v_mfma_scale_f32_16x16x128_f8f6f4 v[186:189], v[164:169], v[8:13], v[64:67], v206, v188 op_sel_hi:[0,0,0] cbsz:2 blgp:2
	v_mfma_scale_f32_16x16x128_f8f6f4 v[220:223], v[158:163], v[14:19], v[60:63], v202, v192 op_sel_hi:[0,0,0] cbsz:2 blgp:2
	v_mfma_scale_f32_16x16x128_f8f6f4 v[190:193], v[164:169], v[14:19], v[48:51], v206, v192 op_sel_hi:[0,0,0] cbsz:2 blgp:2
	v_mfma_scale_f32_16x16x128_f8f6f4 v[202:205], v[158:163], v[20:25], v[40:43], v202, v218 op_sel_hi:[0,0,0] cbsz:2 blgp:2
	v_mfma_scale_f32_16x16x128_f8f6f4 v[216:219], v[164:169], v[20:25], v[36:39], v206, v218 op_sel_hi:[0,0,0] cbsz:2 blgp:2
	s_barrier
	s_mov_b32 m0, s40
	ds_read_b128 v[36:39], v252
	ds_read_b128 v[52:55], v252 offset:1024
	ds_read_b128 v[42:45], v252 offset:2048
	ds_read_b128 v[64:67], v252 offset:3072
	ds_read_b128 v[146:149], v253
	ds_read_b128 v[228:231], v253 offset:1024
	ds_read_b128 v[152:155], v253 offset:2048
	ds_read_b128 v[232:235], v253 offset:3072
	ds_read_b128 v[6:9], v144 offset:32768
	ds_read_b128 v[10:13], v144 offset:33792
	ds_read_b128 v[14:17], v144 offset:34816
	ds_read_b128 v[18:21], v144 offset:35840
	ds_read_b128 v[22:25], v144 offset:36864
	ds_read_b128 v[26:29], v144 offset:37888
	global_load_lds_dwordx4 v[248:249], off
	s_mov_b32 m0, s41
	ds_read_b128 v[48:51], v144 offset:38912
	ds_read_b128 v[60:63], v144 offset:39936
	global_load_lds_dwordx4 v[250:251], off
	s_waitcnt vmcnt(8)
	s_waitcnt lgkmcnt(0)
	s_barrier
	s_waitcnt lgkmcnt(0)
	v_mov_b32_e32 v40, v52
	v_mov_b32_e32 v41, v53
	v_mov_b32_e32 v46, v64
	v_mov_b32_e32 v47, v65
	v_mov_b32_e32 v52, v60
	v_mov_b32_e32 v53, v61
	v_mfma_scale_f32_16x16x128_f8f6f4 v[128:131], v[36:41], v[6:11], v[128:131], v54, v12 op_sel_hi:[0,0,0] cbsz:2 blgp:2
	v_mfma_scale_f32_16x16x128_f8f6f4 v[124:127], v[42:47], v[6:11], v[124:127], v66, v12 op_sel_hi:[0,0,0] cbsz:2 blgp:2
	v_mfma_scale_f32_16x16x128_f8f6f4 v[120:123], v[36:41], v[14:19], v[120:123], v54, v20 op_sel_hi:[0,0,0] cbsz:2 blgp:2
	v_mfma_scale_f32_16x16x128_f8f6f4 v[116:119], v[42:47], v[14:19], v[116:119], v66, v20 op_sel_hi:[0,0,0] cbsz:2 blgp:2
	s_add_i32 s100, s56, s24
	s_add_i32 s101, s57, s24
	s_add_i32 s56, s57, s24
	v_lshl_add_u64 v[240:241], v[236:237], 0, s[22:23]
	v_lshl_add_u64 v[242:243], v[236:237], 0, s[26:27]
	v_lshl_add_u64 v[244:245], v[236:237], 0, s[30:31]
	v_lshl_add_u64 v[246:247], v[236:237], 0, s[34:35]
	v_lshl_add_u64 v[248:249], v[238:239], 0, s[22:23]
	v_lshl_add_u64 v[250:251], v[238:239], 0, s[26:27]
	v_mfma_scale_f32_16x16x128_f8f6f4 v[112:115], v[36:41], v[22:27], v[112:115], v54, v28 op_sel_hi:[0,0,0] cbsz:2 blgp:2
	v_mfma_scale_f32_16x16x128_f8f6f4 v[108:111], v[42:47], v[22:27], v[108:111], v66, v28 op_sel_hi:[0,0,0] cbsz:2 blgp:2
	v_mfma_scale_f32_16x16x128_f8f6f4 v[104:107], v[36:41], v[48:53], v[104:107], v54, v62 op_sel_hi:[0,0,0] cbsz:2 blgp:2
	v_mfma_scale_f32_16x16x128_f8f6f4 v[100:103], v[42:47], v[48:53], v[100:103], v66, v62 op_sel_hi:[0,0,0] cbsz:2 blgp:2
	v_mov_b32_e32 v150, v228
	v_mov_b32_e32 v151, v229
	v_mov_b32_e32 v156, v232
	v_mov_b32_e32 v157, v233
	v_mfma_scale_f32_16x16x128_f8f6f4 v[2:5], v[146:151], v[6:11], v[224:227], v230, v12 op_sel_hi:[0,0,0] cbsz:2 blgp:2
	s_nop 0
	v_mfma_scale_f32_16x16x128_f8f6f4 v[6:9], v[152:157], v[6:11], v[170:173], v234, v12 op_sel_hi:[0,0,0] cbsz:2 blgp:2
	v_mfma_scale_f32_16x16x128_f8f6f4 v[10:13], v[146:151], v[14:19], v[208:211], v230, v20 op_sel_hi:[0,0,0] cbsz:2 blgp:2
	v_mfma_scale_f32_16x16x128_f8f6f4 v[14:17], v[152:157], v[14:19], v[174:177], v234, v20 op_sel_hi:[0,0,0] cbsz:2 blgp:2
	v_mfma_scale_f32_16x16x128_f8f6f4 v[18:21], v[146:151], v[22:27], v[178:181], v230, v28 op_sel_hi:[0,0,0] cbsz:2 blgp:2
	v_mfma_scale_f32_16x16x128_f8f6f4 v[22:25], v[152:157], v[22:27], v[182:185], v234, v28 op_sel_hi:[0,0,0] cbsz:2 blgp:2
	v_mfma_scale_f32_16x16x128_f8f6f4 v[26:29], v[146:151], v[48:53], v[212:215], v230, v62 op_sel_hi:[0,0,0] cbsz:2 blgp:2
	v_mfma_scale_f32_16x16x128_f8f6f4 v[30:33], v[152:157], v[48:53], v[30:33], v234, v62 op_sel_hi:[0,0,0] cbsz:2 blgp:2
	s_barrier
	s_mov_b32 m0, s100
	ds_read_b128 v[60:63], v144 offset:49152
	ds_read_b128 v[48:51], v144 offset:50176
	ds_read_b128 v[158:161], v144 offset:51200
	global_load_lds_dwordx4 v[240:241], off
	s_add_i32 m0, s100, 0x2000
	ds_read_b128 v[174:177], v144 offset:52224
	global_load_lds_dwordx4 v[242:243], off
	s_mov_b32 m0, s101
	ds_read_b128 v[164:167], v144 offset:53248
	global_load_lds_dwordx4 v[244:245], off
	s_add_i32 m0, s101, 0x2000
	ds_read_b128 v[178:181], v144 offset:54272
	global_load_lds_dwordx4 v[246:247], off
	s_mov_b32 m0, s43
	ds_read_b128 v[170:173], v144 offset:55296
	global_load_lds_dwordx4 v[248:249], off
	s_mov_b32 m0, s50
	ds_read_b128 v[182:185], v144 offset:56320
	global_load_lds_dwordx4 v[250:251], off
	s_waitcnt vmcnt(8)
	s_waitcnt lgkmcnt(0)
	s_barrier
	s_waitcnt lgkmcnt(0)
	v_mov_b32_e32 v64, v48
	v_mov_b32_e32 v65, v49
	v_mov_b32_e32 v162, v174
	v_mov_b32_e32 v163, v175
	v_mov_b32_e32 v168, v178
	v_mov_b32_e32 v169, v179
	v_mov_b32_e32 v174, v182
	v_mov_b32_e32 v175, v183
	v_mfma_scale_f32_16x16x128_f8f6f4 v[96:99], v[36:41], v[60:65], v[96:99], v54, v50 op_sel_hi:[0,0,0] cbsz:2 blgp:2
	v_mfma_scale_f32_16x16x128_f8f6f4 v[92:95], v[42:47], v[60:65], v[92:95], v66, v50 op_sel_hi:[0,0,0] cbsz:2 blgp:2
	v_mfma_scale_f32_16x16x128_f8f6f4 v[80:83], v[36:41], v[158:163], v[80:83], v54, v176 op_sel_hi:[0,0,0] cbsz:2 blgp:2
	v_mfma_scale_f32_16x16x128_f8f6f4 v[76:79], v[42:47], v[158:163], v[76:79], v66, v176 op_sel_hi:[0,0,0] cbsz:2 blgp:2
	s_add_i32 s86, s86, 2
	s_add_u32 s54, s54, 0x100
	s_addc_u32 s55, s55, 0
	s_add_u32 s84, s84, 0x100
	s_addc_u32 s85, s85, 0
	v_mfma_scale_f32_16x16x128_f8f6f4 v[68:71], v[36:41], v[164:169], v[68:71], v54, v180 op_sel_hi:[0,0,0] cbsz:2 blgp:2
	v_mfma_scale_f32_16x16x128_f8f6f4 v[56:59], v[42:47], v[164:169], v[56:59], v66, v180 op_sel_hi:[0,0,0] cbsz:2 blgp:2
	v_mfma_scale_f32_16x16x128_f8f6f4 v[52:55], v[36:41], v[170:175], v[194:197], v54, v184 op_sel_hi:[0,0,0] cbsz:2 blgp:2
	v_mfma_scale_f32_16x16x128_f8f6f4 v[44:47], v[42:47], v[170:175], v[198:201], v66, v184 op_sel_hi:[0,0,0] cbsz:2 blgp:2
	v_mfma_scale_f32_16x16x128_f8f6f4 v[88:91], v[146:151], v[60:65], v[88:91], v230, v50 op_sel_hi:[0,0,0] cbsz:2 blgp:2
	v_mfma_scale_f32_16x16x128_f8f6f4 v[84:87], v[152:157], v[60:65], v[84:87], v234, v50 op_sel_hi:[0,0,0] cbsz:2 blgp:2
	v_mfma_scale_f32_16x16x128_f8f6f4 v[72:75], v[146:151], v[158:163], v[72:75], v230, v176 op_sel_hi:[0,0,0] cbsz:2 blgp:2
	v_mfma_scale_f32_16x16x128_f8f6f4 v[64:67], v[152:157], v[158:163], v[186:189], v234, v176 op_sel_hi:[0,0,0] cbsz:2 blgp:2
	v_mfma_scale_f32_16x16x128_f8f6f4 v[60:63], v[146:151], v[164:169], v[220:223], v230, v180 op_sel_hi:[0,0,0] cbsz:2 blgp:2
	v_mfma_scale_f32_16x16x128_f8f6f4 v[48:51], v[152:157], v[164:169], v[190:193], v234, v180 op_sel_hi:[0,0,0] cbsz:2 blgp:2
	v_mfma_scale_f32_16x16x128_f8f6f4 v[40:43], v[146:151], v[170:175], v[202:205], v230, v184 op_sel_hi:[0,0,0] cbsz:2 blgp:2
	v_mfma_scale_f32_16x16x128_f8f6f4 v[36:39], v[152:157], v[170:175], v[216:219], v234, v184 op_sel_hi:[0,0,0] cbsz:2 blgp:2
	s_barrier
	s_cmp_gt_u32 s86, 13
	s_cbranch_scc0 .LBB0_991
	s_setprio 0
	s_and_b64 vcc, exec, s[36:37]
	s_cbranch_vccz .LBB0_994
	s_barrier

.LBB0_1073:
	s_add_u32 s48, s48, 0xb0080
	s_addc_u32 s49, s49, 0
	s_add_u32 s4, s52, 0x100
	v_mov_b32_e32 v2, 0
	s_addc_u32 s5, s53, 0
	s_mov_b32 s63, -2
	v_mov_b32_e32 v3, v2
	v_mov_b32_e32 v4, v2
	v_mov_b32_e32 v5, v2
	v_mov_b32_e32 v6, v2
	v_mov_b32_e32 v7, v2
	v_mov_b32_e32 v8, v2
	v_mov_b32_e32 v9, v2
	v_mov_b32_e32 v18, v2
	v_mov_b32_e32 v19, v2
	v_mov_b32_e32 v20, v2
	v_mov_b32_e32 v21, v2
	v_mov_b32_e32 v22, v2
	v_mov_b32_e32 v23, v2
	v_mov_b32_e32 v24, v2
	v_mov_b32_e32 v25, v2
	v_mov_b32_e32 v34, v2
	v_mov_b32_e32 v35, v2
	v_mov_b32_e32 v36, v2
	v_mov_b32_e32 v37, v2
	v_mov_b32_e32 v38, v2
	v_mov_b32_e32 v39, v2
	v_mov_b32_e32 v40, v2
	v_mov_b32_e32 v41, v2
	v_mov_b32_e32 v50, v2
	v_mov_b32_e32 v51, v2
	v_mov_b32_e32 v52, v2
	v_mov_b32_e32 v53, v2
	v_mov_b32_e32 v54, v2
	v_mov_b32_e32 v55, v2
	v_mov_b32_e32 v56, v2
	v_mov_b32_e32 v57, v2
	v_mov_b32_e32 v10, v2
	v_mov_b32_e32 v11, v2
	v_mov_b32_e32 v12, v2
	v_mov_b32_e32 v13, v2
	v_mov_b32_e32 v14, v2
	v_mov_b32_e32 v15, v2
	v_mov_b32_e32 v16, v2
	v_mov_b32_e32 v17, v2
	v_mov_b32_e32 v26, v2
	v_mov_b32_e32 v27, v2
	v_mov_b32_e32 v28, v2
	v_mov_b32_e32 v29, v2
	v_mov_b32_e32 v30, v2
	v_mov_b32_e32 v31, v2
	v_mov_b32_e32 v32, v2
	v_mov_b32_e32 v33, v2
	v_mov_b32_e32 v42, v2
	v_mov_b32_e32 v43, v2
	v_mov_b32_e32 v44, v2
	v_mov_b32_e32 v45, v2
	v_mov_b32_e32 v46, v2
	v_mov_b32_e32 v47, v2
	v_mov_b32_e32 v48, v2
	v_mov_b32_e32 v49, v2
	v_mov_b32_e32 v58, v2
	v_mov_b32_e32 v59, v2
	v_mov_b32_e32 v60, v2
	v_mov_b32_e32 v61, v2
	v_mov_b32_e32 v62, v2
	v_mov_b32_e32 v63, v2
	v_mov_b32_e32 v64, v2
	v_mov_b32_e32 v65, v2
	v_mov_b32_e32 v66, v2
	v_mov_b32_e32 v67, v2
	v_mov_b32_e32 v68, v2
	v_mov_b32_e32 v69, v2
	v_mov_b32_e32 v70, v2
	v_mov_b32_e32 v71, v2
	v_mov_b32_e32 v72, v2
	v_mov_b32_e32 v73, v2
	v_mov_b32_e32 v82, v2
	v_mov_b32_e32 v83, v2
	v_mov_b32_e32 v84, v2
	v_mov_b32_e32 v85, v2
	v_mov_b32_e32 v86, v2
	v_mov_b32_e32 v87, v2
	v_mov_b32_e32 v88, v2
	v_mov_b32_e32 v89, v2
	v_mov_b32_e32 v98, v2
	v_mov_b32_e32 v99, v2
	v_mov_b32_e32 v100, v2
	v_mov_b32_e32 v101, v2
	v_mov_b32_e32 v102, v2
	v_mov_b32_e32 v103, v2
	v_mov_b32_e32 v104, v2
	v_mov_b32_e32 v105, v2
	v_mov_b32_e32 v146, v2
	v_mov_b32_e32 v147, v2
	v_mov_b32_e32 v148, v2
	v_mov_b32_e32 v149, v2
	v_mov_b32_e32 v150, v2
	v_mov_b32_e32 v151, v2
	v_mov_b32_e32 v152, v2
	v_mov_b32_e32 v153, v2
	v_mov_b32_e32 v74, v2
	v_mov_b32_e32 v75, v2
	v_mov_b32_e32 v76, v2
	v_mov_b32_e32 v77, v2
	v_mov_b32_e32 v78, v2
	v_mov_b32_e32 v79, v2
	v_mov_b32_e32 v80, v2
	v_mov_b32_e32 v81, v2
	v_mov_b32_e32 v90, v2
	v_mov_b32_e32 v91, v2
	v_mov_b32_e32 v92, v2
	v_mov_b32_e32 v93, v2
	v_mov_b32_e32 v94, v2
	v_mov_b32_e32 v95, v2
	v_mov_b32_e32 v96, v2
	v_mov_b32_e32 v97, v2
	v_mov_b32_e32 v106, v2
	v_mov_b32_e32 v107, v2
	v_mov_b32_e32 v108, v2
	v_mov_b32_e32 v109, v2
	v_mov_b32_e32 v110, v2
	v_mov_b32_e32 v111, v2
	v_mov_b32_e32 v112, v2
	v_mov_b32_e32 v113, v2
	v_mov_b32_e32 v154, v2
	v_mov_b32_e32 v155, v2
	v_mov_b32_e32 v156, v2
	v_mov_b32_e32 v157, v2
	v_mov_b32_e32 v158, v2
	v_mov_b32_e32 v159, v2
	v_mov_b32_e32 v160, v2
	v_mov_b32_e32 v161, v2
	v_readfirstlane_b32 s100, v0
	s_bitcmp1_b32 s100, 8
	s_cbranch_scc0 .Lfp6_prio_skip1
	s_setprio 1
.Lfp6_prio_skip1:
.LBB0_1074:
	ds_read_b128 v[114:117], v176
	ds_read_b128 v[142:145], v176 offset:1024
	ds_read_b128 v[120:123], v176 offset:2048
	ds_read_b128 v[172:175], v176 offset:3072
	ds_read_b128 v[126:129], v177
	ds_read_b128 v[198:201], v177 offset:1024
	ds_read_b128 v[132:135], v177 offset:2048
	ds_read_b128 v[202:205], v177 offset:3072
	s_add_u32 s52, s48, 0xfff50080
	s_addc_u32 s53, s49, -1
	s_cmp_eq_u32 s63, 40
	s_cselect_b32 s53, s9, s53
	s_cselect_b32 s52, s8, s52
	s_cselect_b32 s55, s47, s5
	s_cselect_b32 s54, s46, s4
	v_lshl_add_u64 v[118:119], s[48:49], 0, v[166:167]
	s_add_i32 m0, s28, 0xc000
	ds_read_b128 v[138:141], v178
	ds_read_b128 v[206:209], v178 offset:1024
	ds_read_b128 v[180:183], v178 offset:2048
	ds_read_b128 v[210:213], v178 offset:3072
	ds_read_b128 v[186:189], v178 offset:4096
	ds_read_b128 v[214:217], v178 offset:5120
	ds_read_b128 v[192:195], v178 offset:6144
	ds_read_b128 v[218:221], v178 offset:7168
	global_load_lds_dwordx4 v[118:119], off
	v_lshl_add_u64 v[118:119], v[118:119], 0, s[12:13]
	s_add_i32 m0, s28, 0xe000
	s_nop 0
	global_load_lds_dwordx4 v[118:119], off
	s_waitcnt vmcnt(8)
	s_waitcnt lgkmcnt(0)
	s_barrier
	s_waitcnt lgkmcnt(0)
	v_mov_b32_e32 v118, v142
	v_mov_b32_e32 v119, v143
	v_mov_b32_e32 v124, v172
	v_mov_b32_e32 v125, v173
	v_mov_b32_e32 v142, v206
	v_mov_b32_e32 v143, v207
	v_mov_b32_e32 v184, v210
	v_mov_b32_e32 v185, v211
	v_mov_b32_e32 v190, v214
	v_mov_b32_e32 v191, v215
	v_mfma_scale_f32_16x16x128_f8f6f4 v[158:161], v[114:119], v[138:143], v[158:161], v144, v208 op_sel_hi:[0,0,0] cbsz:2 blgp:2
	v_mov_b32_e32 v196, v218
	v_mov_b32_e32 v197, v219
	v_mfma_scale_f32_16x16x128_f8f6f4 v[154:157], v[120:125], v[138:143], v[154:157], v174, v208 op_sel_hi:[0,0,0] cbsz:2 blgp:2
	v_mfma_scale_f32_16x16x128_f8f6f4 v[110:113], v[114:119], v[180:185], v[110:113], v144, v212 op_sel_hi:[0,0,0] cbsz:2 blgp:2
	v_mfma_scale_f32_16x16x128_f8f6f4 v[106:109], v[120:125], v[180:185], v[106:109], v174, v212 op_sel_hi:[0,0,0] cbsz:2 blgp:2
	v_mfma_scale_f32_16x16x128_f8f6f4 v[94:97], v[114:119], v[186:191], v[94:97], v144, v216 op_sel_hi:[0,0,0] cbsz:2 blgp:2
	v_mfma_scale_f32_16x16x128_f8f6f4 v[90:93], v[120:125], v[186:191], v[90:93], v174, v216 op_sel_hi:[0,0,0] cbsz:2 blgp:2
	v_mfma_scale_f32_16x16x128_f8f6f4 v[222:225], v[114:119], v[192:197], v[78:81], v144, v220 op_sel_hi:[0,0,0] cbsz:2 blgp:2
	v_mfma_scale_f32_16x16x128_f8f6f4 v[226:229], v[120:125], v[192:197], v[74:77], v174, v220 op_sel_hi:[0,0,0] cbsz:2 blgp:2
	v_mov_b32_e32 v130, v198
	v_mov_b32_e32 v131, v199
	v_mov_b32_e32 v136, v202
	v_mov_b32_e32 v137, v203
	v_mfma_scale_f32_16x16x128_f8f6f4 v[150:153], v[126:131], v[138:143], v[150:153], v200, v208 op_sel_hi:[0,0,0] cbsz:2 blgp:2
	v_mfma_scale_f32_16x16x128_f8f6f4 v[102:105], v[126:131], v[180:185], v[102:105], v200, v212 op_sel_hi:[0,0,0] cbsz:2 blgp:2
	v_mfma_scale_f32_16x16x128_f8f6f4 v[98:101], v[132:137], v[180:185], v[98:101], v204, v212 op_sel_hi:[0,0,0] cbsz:2 blgp:2
	v_mfma_scale_f32_16x16x128_f8f6f4 v[138:141], v[132:137], v[138:143], v[146:149], v204, v208 op_sel_hi:[0,0,0] cbsz:2 blgp:2
	v_mfma_scale_f32_16x16x128_f8f6f4 v[180:183], v[126:131], v[186:191], v[86:89], v200, v216 op_sel_hi:[0,0,0] cbsz:2 blgp:2
	v_mfma_scale_f32_16x16x128_f8f6f4 v[184:187], v[132:137], v[186:191], v[82:85], v204, v216 op_sel_hi:[0,0,0] cbsz:2 blgp:2
	v_mfma_scale_f32_16x16x128_f8f6f4 v[188:191], v[126:131], v[192:197], v[70:73], v200, v220 op_sel_hi:[0,0,0] cbsz:2 blgp:2
	v_mfma_scale_f32_16x16x128_f8f6f4 v[192:195], v[132:137], v[192:197], v[66:69], v204, v220 op_sel_hi:[0,0,0] cbsz:2 blgp:2
	s_barrier
	v_lshl_add_u64 v[250:251], s[54:55], 0, v[164:165]
	s_add_i32 s54, s64, s25
	s_mov_b32 m0, s54
	ds_read_b128 v[66:69], v178 offset:16384
	ds_read_b128 v[146:149], v178 offset:17408
	ds_read_b128 v[72:75], v178 offset:18432
	ds_read_b128 v[196:199], v178 offset:19456
	ds_read_b128 v[78:81], v178 offset:20480
	ds_read_b128 v[206:209], v178 offset:21504
	ds_read_b128 v[84:87], v178 offset:22528
	ds_read_b128 v[210:213], v178 offset:23552
	global_load_lds_dwordx4 v[250:251], off
	v_lshl_add_u64 v[70:71], v[250:251], 0, s[12:13]
	s_add_i32 m0, s54, 0x2000
	s_add_i32 s54, s65, s25
	global_load_lds_dwordx4 v[70:71], off
	v_lshl_add_u64 v[70:71], v[250:251], 0, s[14:15]
	s_mov_b32 m0, s54
	v_lshl_add_u64 v[252:253], s[52:53], 0, v[162:163]
	global_load_lds_dwordx4 v[70:71], off
	v_lshl_add_u64 v[70:71], v[250:251], 0, s[16:17]
	s_add_i32 m0, s54, 0x2000
	s_nop 0
	global_load_lds_dwordx4 v[70:71], off
	s_mov_b32 m0, s28
	v_lshl_add_u64 v[70:71], v[252:253], 0, s[12:13]
	global_load_lds_dwordx4 v[252:253], off
	s_mov_b32 m0, s29
	s_nop 0
	global_load_lds_dwordx4 v[70:71], off
	s_waitcnt vmcnt(8)
	s_waitcnt lgkmcnt(0)
	s_barrier
	s_waitcnt lgkmcnt(0)
	v_mov_b32_e32 v70, v146
	v_mov_b32_e32 v71, v147
	v_mov_b32_e32 v76, v196
	v_mov_b32_e32 v77, v197
	v_mfma_scale_f32_16x16x128_f8f6f4 v[62:65], v[114:119], v[66:71], v[62:65], v144, v148 op_sel_hi:[0,0,0] cbsz:2 blgp:2
	v_mov_b32_e32 v82, v206
	v_mov_b32_e32 v83, v207
	v_mov_b32_e32 v88, v210
	v_mfma_scale_f32_16x16x128_f8f6f4 v[58:61], v[120:125], v[66:71], v[58:61], v174, v148 op_sel_hi:[0,0,0] cbsz:2 blgp:2
	v_mov_b32_e32 v89, v211
	v_mfma_scale_f32_16x16x128_f8f6f4 v[46:49], v[114:119], v[72:77], v[46:49], v144, v198 op_sel_hi:[0,0,0] cbsz:2 blgp:2
	v_mfma_scale_f32_16x16x128_f8f6f4 v[42:45], v[120:125], v[72:77], v[42:45], v174, v198 op_sel_hi:[0,0,0] cbsz:2 blgp:2
	v_mfma_scale_f32_16x16x128_f8f6f4 v[214:217], v[114:119], v[78:83], v[30:33], v144, v208 op_sel_hi:[0,0,0] cbsz:2 blgp:2
	v_mfma_scale_f32_16x16x128_f8f6f4 v[218:221], v[120:125], v[78:83], v[26:29], v174, v208 op_sel_hi:[0,0,0] cbsz:2 blgp:2
	v_mfma_scale_f32_16x16x128_f8f6f4 v[230:233], v[114:119], v[84:89], v[14:17], v144, v212 op_sel_hi:[0,0,0] cbsz:2 blgp:2
	v_mfma_scale_f32_16x16x128_f8f6f4 v[172:175], v[120:125], v[84:89], v[10:13], v174, v212 op_sel_hi:[0,0,0] cbsz:2 blgp:2
	v_mfma_scale_f32_16x16x128_f8f6f4 v[54:57], v[126:131], v[66:71], v[54:57], v200, v148 op_sel_hi:[0,0,0] cbsz:2 blgp:2
	v_mfma_scale_f32_16x16x128_f8f6f4 v[50:53], v[132:137], v[66:71], v[50:53], v204, v148 op_sel_hi:[0,0,0] cbsz:2 blgp:2
	v_mfma_scale_f32_16x16x128_f8f6f4 v[38:41], v[126:131], v[72:77], v[38:41], v200, v198 op_sel_hi:[0,0,0] cbsz:2 blgp:2
	v_mfma_scale_f32_16x16x128_f8f6f4 v[196:199], v[132:137], v[72:77], v[34:37], v204, v198 op_sel_hi:[0,0,0] cbsz:2 blgp:2
	v_mfma_scale_f32_16x16x128_f8f6f4 v[234:237], v[126:131], v[78:83], v[22:25], v200, v208 op_sel_hi:[0,0,0] cbsz:2 blgp:2
	v_mfma_scale_f32_16x16x128_f8f6f4 v[206:209], v[132:137], v[78:83], v[18:21], v204, v208 op_sel_hi:[0,0,0] cbsz:2 blgp:2
	v_mfma_scale_f32_16x16x128_f8f6f4 v[200:203], v[126:131], v[84:89], v[6:9], v200, v212 op_sel_hi:[0,0,0] cbsz:2 blgp:2
	v_mfma_scale_f32_16x16x128_f8f6f4 v[210:213], v[132:137], v[84:89], v[2:5], v204, v212 op_sel_hi:[0,0,0] cbsz:2 blgp:2
	s_barrier
	s_add_i32 s52, 0, 0x18000
	v_add_u32_e32 v6, s52, v1
	s_add_i32 s53, 0, 0x1c000
	ds_read_b128 v[2:5], v6
	ds_read_b128 v[142:145], v6 offset:1024
	ds_read_b128 v[8:11], v6 offset:2048
	ds_read_b128 v[238:241], v6 offset:3072
	v_add_u32_e32 v6, s53, v1
	ds_read_b128 v[114:117], v6
	ds_read_b128 v[242:245], v6 offset:1024
	ds_read_b128 v[120:123], v6 offset:2048
	ds_read_b128 v[246:249], v6 offset:3072
	s_mov_b32 m0, s33
	v_lshl_add_u64 v[6:7], v[252:253], 0, s[14:15]
	ds_read_b128 v[14:17], v178 offset:32768
	ds_read_b128 v[66:69], v178 offset:33792
	ds_read_b128 v[20:23], v178 offset:34816
	ds_read_b128 v[70:73], v178 offset:35840
	ds_read_b128 v[26:29], v178 offset:36864
	ds_read_b128 v[80:83], v178 offset:37888
	ds_read_b128 v[32:35], v178 offset:38912
	ds_read_b128 v[124:127], v178 offset:39936
	global_load_lds_dwordx4 v[6:7], off
	v_lshl_add_u64 v[6:7], v[252:253], 0, s[16:17]
	s_mov_b32 m0, s40
	s_nop 0
	global_load_lds_dwordx4 v[6:7], off
	s_waitcnt vmcnt(8)
	s_waitcnt lgkmcnt(0)
	s_barrier
	s_waitcnt lgkmcnt(0)
	v_mov_b32_e32 v6, v142
	v_mov_b32_e32 v7, v143
	v_mov_b32_e32 v12, v238
	v_mov_b32_e32 v13, v239
	v_mov_b32_e32 v18, v66
	v_mov_b32_e32 v19, v67
	v_mov_b32_e32 v24, v70
	v_mov_b32_e32 v25, v71
	v_mov_b32_e32 v30, v80
	v_mov_b32_e32 v31, v81
	v_mov_b32_e32 v36, v124
	v_mov_b32_e32 v37, v125
	v_mfma_scale_f32_16x16x128_f8f6f4 v[158:161], v[2:7], v[14:19], v[158:161], v144, v68 op_sel_hi:[0,0,0] cbsz:2 blgp:2
	v_mfma_scale_f32_16x16x128_f8f6f4 v[154:157], v[8:13], v[14:19], v[154:157], v240, v68 op_sel_hi:[0,0,0] cbsz:2 blgp:2
	v_mfma_scale_f32_16x16x128_f8f6f4 v[110:113], v[2:7], v[20:25], v[110:113], v144, v72 op_sel_hi:[0,0,0] cbsz:2 blgp:2
	v_mfma_scale_f32_16x16x128_f8f6f4 v[106:109], v[8:13], v[20:25], v[106:109], v240, v72 op_sel_hi:[0,0,0] cbsz:2 blgp:2
	v_mfma_scale_f32_16x16x128_f8f6f4 v[94:97], v[2:7], v[26:31], v[94:97], v144, v82 op_sel_hi:[0,0,0] cbsz:2 blgp:2
	v_mfma_scale_f32_16x16x128_f8f6f4 v[90:93], v[8:13], v[26:31], v[90:93], v240, v82 op_sel_hi:[0,0,0] cbsz:2 blgp:2
	v_mfma_scale_f32_16x16x128_f8f6f4 v[78:81], v[2:7], v[32:37], v[222:225], v144, v126 op_sel_hi:[0,0,0] cbsz:2 blgp:2
	v_mfma_scale_f32_16x16x128_f8f6f4 v[74:77], v[8:13], v[32:37], v[226:229], v240, v126 op_sel_hi:[0,0,0] cbsz:2 blgp:2
	v_mov_b32_e32 v118, v242
	v_mov_b32_e32 v119, v243
	v_mov_b32_e32 v124, v246
	v_mov_b32_e32 v125, v247
	v_mfma_scale_f32_16x16x128_f8f6f4 v[150:153], v[114:119], v[14:19], v[150:153], v244, v68 op_sel_hi:[0,0,0] cbsz:2 blgp:2
	s_nop 0
	v_mfma_scale_f32_16x16x128_f8f6f4 v[146:149], v[120:125], v[14:19], v[138:141], v248, v68 op_sel_hi:[0,0,0] cbsz:2 blgp:2
	v_mfma_scale_f32_16x16x128_f8f6f4 v[102:105], v[114:119], v[20:25], v[102:105], v244, v72 op_sel_hi:[0,0,0] cbsz:2 blgp:2
	v_mfma_scale_f32_16x16x128_f8f6f4 v[98:101], v[120:125], v[20:25], v[98:101], v248, v72 op_sel_hi:[0,0,0] cbsz:2 blgp:2
	v_mfma_scale_f32_16x16x128_f8f6f4 v[86:89], v[114:119], v[26:31], v[180:183], v244, v82 op_sel_hi:[0,0,0] cbsz:2 blgp:2
	v_mfma_scale_f32_16x16x128_f8f6f4 v[82:85], v[120:125], v[26:31], v[184:187], v248, v82 op_sel_hi:[0,0,0] cbsz:2 blgp:2
	v_mfma_scale_f32_16x16x128_f8f6f4 v[70:73], v[114:119], v[32:37], v[188:191], v244, v126 op_sel_hi:[0,0,0] cbsz:2 blgp:2
	v_mfma_scale_f32_16x16x128_f8f6f4 v[66:69], v[120:125], v[32:37], v[192:195], v248, v126 op_sel_hi:[0,0,0] cbsz:2 blgp:2
	s_barrier
	s_add_i32 s52, s52, s25
	v_lshl_add_u64 v[14:15], v[250:251], 0, s[26:27]
	s_mov_b32 m0, s52
	ds_read_b128 v[18:21], v178 offset:49152
	ds_read_b128 v[22:25], v178 offset:50176
	ds_read_b128 v[126:129], v178 offset:51200
	ds_read_b128 v[32:35], v178 offset:52224
	ds_read_b128 v[132:135], v178 offset:53248
	ds_read_b128 v[180:183], v178 offset:54272
	ds_read_b128 v[138:141], v178 offset:55296
	ds_read_b128 v[184:187], v178 offset:56320
	global_load_lds_dwordx4 v[14:15], off
	v_lshl_add_u64 v[14:15], v[250:251], 0, s[30:31]
	s_add_i32 m0, s52, 0x2000
	s_add_i32 s52, s53, s25
	global_load_lds_dwordx4 v[14:15], off
	v_lshl_add_u64 v[14:15], v[250:251], 0, s[34:35]
	s_mov_b32 m0, s52
	s_nop 0
	global_load_lds_dwordx4 v[14:15], off
	v_lshl_add_u64 v[14:15], v[250:251], 0, s[36:37]
	s_add_i32 m0, s52, 0x2000
	s_nop 0
	global_load_lds_dwordx4 v[14:15], off
	v_lshl_add_u64 v[14:15], v[252:253], 0, s[26:27]
	s_mov_b32 m0, s43
	s_nop 0
	global_load_lds_dwordx4 v[14:15], off
	v_lshl_add_u64 v[14:15], v[252:253], 0, s[30:31]
	s_mov_b32 m0, s45
	s_nop 0
	global_load_lds_dwordx4 v[14:15], off
	s_waitcnt vmcnt(8)
	s_waitcnt lgkmcnt(0)
	s_barrier
	s_waitcnt lgkmcnt(0)
	v_mov_b32_e32 v130, v32
	v_mov_b32_e32 v131, v33
	v_mov_b32_e32 v136, v180
	v_mov_b32_e32 v137, v181
	v_mov_b32_e32 v142, v184
	v_mov_b32_e32 v143, v185
	v_mfma_scale_f32_16x16x128_f8f6f4 v[62:65], v[2:7], v[18:23], v[62:65], v144, v24 op_sel_hi:[0,0,0] cbsz:2 blgp:2
	v_mfma_scale_f32_16x16x128_f8f6f4 v[58:61], v[8:13], v[18:23], v[58:61], v240, v24 op_sel_hi:[0,0,0] cbsz:2 blgp:2
	v_mfma_scale_f32_16x16x128_f8f6f4 v[46:49], v[2:7], v[126:131], v[46:49], v144, v34 op_sel_hi:[0,0,0] cbsz:2 blgp:2
	v_mfma_scale_f32_16x16x128_f8f6f4 v[42:45], v[8:13], v[126:131], v[42:45], v240, v34 op_sel_hi:[0,0,0] cbsz:2 blgp:2
	v_mfma_scale_f32_16x16x128_f8f6f4 v[30:33], v[2:7], v[132:137], v[214:217], v144, v182 op_sel_hi:[0,0,0] cbsz:2 blgp:2
	v_mfma_scale_f32_16x16x128_f8f6f4 v[26:29], v[8:13], v[132:137], v[218:221], v240, v182 op_sel_hi:[0,0,0] cbsz:2 blgp:2
	v_mfma_scale_f32_16x16x128_f8f6f4 v[14:17], v[2:7], v[138:143], v[230:233], v144, v186 op_sel_hi:[0,0,0] cbsz:2 blgp:2
	v_mfma_scale_f32_16x16x128_f8f6f4 v[10:13], v[8:13], v[138:143], v[172:175], v240, v186 op_sel_hi:[0,0,0] cbsz:2 blgp:2
	v_mfma_scale_f32_16x16x128_f8f6f4 v[54:57], v[114:119], v[18:23], v[54:57], v244, v24 op_sel_hi:[0,0,0] cbsz:2 blgp:2
	v_mfma_scale_f32_16x16x128_f8f6f4 v[50:53], v[120:125], v[18:23], v[50:53], v248, v24 op_sel_hi:[0,0,0] cbsz:2 blgp:2
	v_mfma_scale_f32_16x16x128_f8f6f4 v[38:41], v[114:119], v[126:131], v[38:41], v244, v34 op_sel_hi:[0,0,0] cbsz:2 blgp:2
	v_mfma_scale_f32_16x16x128_f8f6f4 v[34:37], v[120:125], v[126:131], v[196:199], v248, v34 op_sel_hi:[0,0,0] cbsz:2 blgp:2
	v_mfma_scale_f32_16x16x128_f8f6f4 v[22:25], v[114:119], v[132:137], v[234:237], v244, v182 op_sel_hi:[0,0,0] cbsz:2 blgp:2
	v_mfma_scale_f32_16x16x128_f8f6f4 v[18:21], v[120:125], v[132:137], v[206:209], v248, v182 op_sel_hi:[0,0,0] cbsz:2 blgp:2
	v_mfma_scale_f32_16x16x128_f8f6f4 v[6:9], v[114:119], v[138:143], v[200:203], v244, v186 op_sel_hi:[0,0,0] cbsz:2 blgp:2
	v_mfma_scale_f32_16x16x128_f8f6f4 v[2:5], v[120:125], v[138:143], v[210:213], v248, v186 op_sel_hi:[0,0,0] cbsz:2 blgp:2
	s_barrier
	s_add_i32 s63, s63, 2
	s_add_u32 s48, s48, 0x100
	s_addc_u32 s49, s49, 0
	s_add_u32 s4, s4, 0x100
	s_addc_u32 s5, s5, 0
	s_cmp_gt_u32 s63, 41
	s_cbranch_scc0 .LBB0_1074
	s_setprio 0
	s_and_b64 vcc, exec, s[38:39]
	s_cbranch_vccz .LBB0_1077
	s_barrier

.LBB0_2186:
	s_ashr_i32 s35, s34, 31
	s_lshl_b64 s[38:39], s[34:35], 19
	s_add_u32 s38, s1, s38
	s_addc_u32 s39, s2, s39
	s_and_b64 s[44:45], s[52:53], exec
	s_cselect_b32 s35, s39, s49
	s_cselect_b32 s47, s38, s48
	s_ashr_i32 s37, s36, 31
	s_lshl_b64 s[44:45], s[36:37], 19
	s_add_u32 s44, s3, s44
	s_addc_u32 s45, s28, s45
	s_and_b64 s[52:53], s[52:53], exec
	s_cselect_b32 s37, s45, s51
	s_cselect_b32 s65, s44, s50
	s_add_u32 s48, s48, 0x40080
	s_addc_u32 s49, s49, 0
	s_add_u32 s66, s50, 0x100
	v_mov_b32_e32 v36, 0
	s_addc_u32 s67, s51, 0
	s_mov_b32 s76, -2
	v_mov_b32_e32 v37, v36
	v_mov_b32_e32 v38, v36
	v_mov_b32_e32 v39, v36
	v_mov_b32_e32 v40, v36
	v_mov_b32_e32 v41, v36
	v_mov_b32_e32 v42, v36
	v_mov_b32_e32 v43, v36
	v_mov_b32_e32 v48, v36
	v_mov_b32_e32 v49, v36
	v_mov_b32_e32 v50, v36
	v_mov_b32_e32 v51, v36
	v_mov_b32_e32 v60, v36
	v_mov_b32_e32 v61, v36
	v_mov_b32_e32 v62, v36
	v_mov_b32_e32 v63, v36
	v_mov_b32_e32 v64, v36
	v_mov_b32_e32 v65, v36
	v_mov_b32_e32 v66, v36
	v_mov_b32_e32 v67, v36
	v_mov_b32_e32 v72, v36
	v_mov_b32_e32 v73, v36
	v_mov_b32_e32 v74, v36
	v_mov_b32_e32 v75, v36
	v_mov_b32_e32 v84, v36
	v_mov_b32_e32 v85, v36
	v_mov_b32_e32 v86, v36
	v_mov_b32_e32 v87, v36
	v_mov_b32_e32 v88, v36
	v_mov_b32_e32 v89, v36
	v_mov_b32_e32 v90, v36
	v_mov_b32_e32 v91, v36
	v_mov_b32_e32 v44, v36
	v_mov_b32_e32 v45, v36
	v_mov_b32_e32 v46, v36
	v_mov_b32_e32 v47, v36
	v_mov_b32_e32 v52, v36
	v_mov_b32_e32 v53, v36
	v_mov_b32_e32 v54, v36
	v_mov_b32_e32 v55, v36
	v_mov_b32_e32 v56, v36
	v_mov_b32_e32 v57, v36
	v_mov_b32_e32 v58, v36
	v_mov_b32_e32 v59, v36
	v_mov_b32_e32 v68, v36
	v_mov_b32_e32 v69, v36
	v_mov_b32_e32 v70, v36
	v_mov_b32_e32 v71, v36
	v_mov_b32_e32 v76, v36
	v_mov_b32_e32 v77, v36
	v_mov_b32_e32 v78, v36
	v_mov_b32_e32 v79, v36
	v_mov_b32_e32 v80, v36
	v_mov_b32_e32 v81, v36
	v_mov_b32_e32 v82, v36
	v_mov_b32_e32 v83, v36
	v_mov_b32_e32 v92, v36
	v_mov_b32_e32 v93, v36
	v_mov_b32_e32 v94, v36
	v_mov_b32_e32 v95, v36
	v_mov_b32_e32 v96, v36
	v_mov_b32_e32 v97, v36
	v_mov_b32_e32 v98, v36
	v_mov_b32_e32 v99, v36
	v_mov_b32_e32 v30, v36
	v_mov_b32_e32 v31, v36
	v_mov_b32_e32 v32, v36
	v_mov_b32_e32 v33, v36
	v_mov_b32_e32 v26, v36
	v_mov_b32_e32 v27, v36
	v_mov_b32_e32 v28, v36
	v_mov_b32_e32 v29, v36
	v_mov_b32_e32 v22, v36
	v_mov_b32_e32 v23, v36
	v_mov_b32_e32 v24, v36
	v_mov_b32_e32 v25, v36
	v_mov_b32_e32 v18, v36
	v_mov_b32_e32 v19, v36
	v_mov_b32_e32 v20, v36
	v_mov_b32_e32 v21, v36
	v_mov_b32_e32 v14, v36
	v_mov_b32_e32 v15, v36
	v_mov_b32_e32 v16, v36
	v_mov_b32_e32 v17, v36
	v_mov_b32_e32 v10, v36
	v_mov_b32_e32 v11, v36
	v_mov_b32_e32 v12, v36
	v_mov_b32_e32 v13, v36
	v_mov_b32_e32 v6, v36
	v_mov_b32_e32 v7, v36
	v_mov_b32_e32 v8, v36
	v_mov_b32_e32 v9, v36
	v_mov_b32_e32 v2, v36
	v_mov_b32_e32 v3, v36
	v_mov_b32_e32 v4, v36
	v_mov_b32_e32 v5, v36
	v_mov_b32_e32 v100, v36
	v_mov_b32_e32 v101, v36
	v_mov_b32_e32 v102, v36
	v_mov_b32_e32 v103, v36
	v_mov_b32_e32 v104, v36
	v_mov_b32_e32 v105, v36
	v_mov_b32_e32 v106, v36
	v_mov_b32_e32 v107, v36
	v_mov_b32_e32 v108, v36
	v_mov_b32_e32 v109, v36
	v_mov_b32_e32 v110, v36
	v_mov_b32_e32 v111, v36
	v_mov_b32_e32 v112, v36
	v_mov_b32_e32 v113, v36
	v_mov_b32_e32 v114, v36
	v_mov_b32_e32 v115, v36
	v_mov_b32_e32 v116, v36
	v_mov_b32_e32 v117, v36
	v_mov_b32_e32 v118, v36
	v_mov_b32_e32 v119, v36
	v_mov_b32_e32 v120, v36
	v_mov_b32_e32 v121, v36
	v_mov_b32_e32 v122, v36
	v_mov_b32_e32 v123, v36
	v_mov_b32_e32 v124, v36
	v_mov_b32_e32 v125, v36
	v_mov_b32_e32 v126, v36
	v_mov_b32_e32 v127, v36
	v_mov_b32_e32 v128, v36
	v_mov_b32_e32 v129, v36
	v_mov_b32_e32 v130, v36
	v_mov_b32_e32 v131, v36
	v_readfirstlane_b32 s100, v0
	s_bitcmp1_b32 s100, 8
	s_cbranch_scc0 .Lfp6_prio_skip2
	s_setprio 1
.Lfp6_prio_skip2:
.LBB0_2187:
	ds_read_b128 v[142:145], v138
	ds_read_b128 v[188:191], v138 offset:1024
	ds_read_b128 v[148:151], v138 offset:2048
	ds_read_b128 v[192:195], v138 offset:3072
	ds_read_b128 v[154:157], v139
	ds_read_b128 v[196:199], v139 offset:1024
	ds_read_b128 v[160:163], v139 offset:2048
	ds_read_b128 v[200:203], v139 offset:3072
	v_lshl_add_u64 v[146:147], s[48:49], 0, v[136:137]
	s_add_i32 m0, s33, 0xc000
	ds_read_b128 v[166:169], v140
	ds_read_b128 v[204:207], v140 offset:1024
	ds_read_b128 v[172:175], v140 offset:2048
	ds_read_b128 v[208:211], v140 offset:3072
	ds_read_b128 v[178:181], v140 offset:4096
	ds_read_b128 v[212:215], v140 offset:5120
	ds_read_b128 v[184:187], v140 offset:6144
	ds_read_b128 v[216:219], v140 offset:7168
	global_load_lds_dwordx4 v[146:147], off
	s_add_i32 m0, s33, 0xe000
	v_lshl_add_u64 v[146:147], v[146:147], 0, s[6:7]
	global_load_lds_dwordx4 v[146:147], off
	s_waitcnt vmcnt(8)
	s_waitcnt lgkmcnt(0)
	s_barrier
	s_waitcnt lgkmcnt(0)
	v_mov_b32_e32 v146, v188
	v_mov_b32_e32 v147, v189
	v_mov_b32_e32 v152, v192
	v_mov_b32_e32 v153, v193
	v_mov_b32_e32 v170, v204
	v_mov_b32_e32 v171, v205
	v_mov_b32_e32 v176, v208
	v_mov_b32_e32 v177, v209
	v_mov_b32_e32 v182, v212
	v_mov_b32_e32 v183, v213
	v_mov_b32_e32 v188, v216
	v_mov_b32_e32 v189, v217
	v_mfma_scale_f32_16x16x128_f8f6f4 v[128:131], v[142:147], v[166:171], v[128:131], v190, v206 op_sel_hi:[0,0,0] cbsz:2 blgp:2
	v_mfma_scale_f32_16x16x128_f8f6f4 v[124:127], v[148:153], v[166:171], v[124:127], v194, v206 op_sel_hi:[0,0,0] cbsz:2 blgp:2
	v_mfma_scale_f32_16x16x128_f8f6f4 v[120:123], v[142:147], v[172:177], v[120:123], v190, v210 op_sel_hi:[0,0,0] cbsz:2 blgp:2
	v_mfma_scale_f32_16x16x128_f8f6f4 v[116:119], v[148:153], v[172:177], v[116:119], v194, v210 op_sel_hi:[0,0,0] cbsz:2 blgp:2
	s_add_u32 s50, s48, 0xfffc0080
	s_addc_u32 s51, s49, -1
	s_cmp_eq_u32 s76, 12
	s_cselect_b32 s51, s35, s51
	s_cselect_b32 s50, s47, s50
	s_cselect_b32 s53, s37, s67
	s_cselect_b32 s52, s65, s66
	s_add_i32 s100, s57, s29
	s_add_i32 s101, s58, s29
	v_lshl_add_u64 v[232:233], s[52:53], 0, v[132:133]
	v_lshl_add_u64 v[234:235], s[50:51], 0, v[134:135]
	v_lshl_add_u64 v[240:241], v[232:233], 0, s[6:7]
	v_lshl_add_u64 v[242:243], v[232:233], 0, s[8:9]
	v_lshl_add_u64 v[244:245], v[232:233], 0, s[10:11]
	v_lshl_add_u64 v[246:247], v[234:235], 0, s[6:7]
	v_mfma_scale_f32_16x16x128_f8f6f4 v[112:115], v[142:147], v[178:183], v[112:115], v190, v214 op_sel_hi:[0,0,0] cbsz:2 blgp:2
	v_mfma_scale_f32_16x16x128_f8f6f4 v[108:111], v[148:153], v[178:183], v[108:111], v194, v214 op_sel_hi:[0,0,0] cbsz:2 blgp:2
	v_mfma_scale_f32_16x16x128_f8f6f4 v[104:107], v[142:147], v[184:189], v[104:107], v190, v218 op_sel_hi:[0,0,0] cbsz:2 blgp:2
	v_mfma_scale_f32_16x16x128_f8f6f4 v[100:103], v[148:153], v[184:189], v[100:103], v194, v218 op_sel_hi:[0,0,0] cbsz:2 blgp:2
	v_mov_b32_e32 v164, v200
	v_mov_b32_e32 v165, v201
	v_mov_b32_e32 v158, v196
	v_mov_b32_e32 v159, v197
	v_mfma_scale_f32_16x16x128_f8f6f4 v[30:33], v[160:165], v[184:189], v[30:33], v202, v218 op_sel_hi:[0,0,0] cbsz:2 blgp:2
	s_nop 0
	v_mfma_scale_f32_16x16x128_f8f6f4 v[220:223], v[154:159], v[166:171], v[2:5], v198, v206 op_sel_hi:[0,0,0] cbsz:2 blgp:2
	v_mfma_scale_f32_16x16x128_f8f6f4 v[166:169], v[160:165], v[166:171], v[6:9], v202, v206 op_sel_hi:[0,0,0] cbsz:2 blgp:2
	v_mfma_scale_f32_16x16x128_f8f6f4 v[204:207], v[154:159], v[172:177], v[10:13], v198, v210 op_sel_hi:[0,0,0] cbsz:2 blgp:2
	v_mfma_scale_f32_16x16x128_f8f6f4 v[170:173], v[160:165], v[172:177], v[14:17], v202, v210 op_sel_hi:[0,0,0] cbsz:2 blgp:2
	v_mfma_scale_f32_16x16x128_f8f6f4 v[174:177], v[154:159], v[178:183], v[18:21], v198, v214 op_sel_hi:[0,0,0] cbsz:2 blgp:2
	v_mfma_scale_f32_16x16x128_f8f6f4 v[178:181], v[160:165], v[178:183], v[22:25], v202, v214 op_sel_hi:[0,0,0] cbsz:2 blgp:2
	v_mfma_scale_f32_16x16x128_f8f6f4 v[208:211], v[154:159], v[184:189], v[26:29], v198, v218 op_sel_hi:[0,0,0] cbsz:2 blgp:2
	s_barrier
	s_mov_b32 m0, s100
	ds_read_b128 v[2:5], v140 offset:16384
	ds_read_b128 v[24:27], v140 offset:17408
	ds_read_b128 v[8:11], v140 offset:18432
	global_load_lds_dwordx4 v[232:233], off
	s_add_i32 m0, s100, 0x2000
	ds_read_b128 v[182:185], v140 offset:19456
	global_load_lds_dwordx4 v[240:241], off
	s_mov_b32 m0, s101
	ds_read_b128 v[14:17], v140 offset:20480
	global_load_lds_dwordx4 v[242:243], off
	s_add_i32 m0, s101, 0x2000
	ds_read_b128 v[186:189], v140 offset:21504
	global_load_lds_dwordx4 v[244:245], off
	s_mov_b32 m0, s33
	ds_read_b128 v[20:23], v140 offset:22528
	global_load_lds_dwordx4 v[234:235], off
	s_mov_b32 m0, s40
	ds_read_b128 v[212:215], v140 offset:23552
	global_load_lds_dwordx4 v[246:247], off
	s_waitcnt vmcnt(8)
	s_waitcnt lgkmcnt(0)
	s_barrier
	s_waitcnt lgkmcnt(0)
	v_mov_b32_e32 v6, v24
	v_mov_b32_e32 v7, v25
	v_mov_b32_e32 v12, v182
	v_mov_b32_e32 v13, v183
	v_mov_b32_e32 v18, v186
	v_mov_b32_e32 v19, v187
	v_mfma_scale_f32_16x16x128_f8f6f4 v[96:99], v[142:147], v[2:7], v[96:99], v190, v26 op_sel_hi:[0,0,0] cbsz:2 blgp:2
	v_mov_b32_e32 v24, v212
	v_mov_b32_e32 v25, v213
	v_mfma_scale_f32_16x16x128_f8f6f4 v[92:95], v[148:153], v[2:7], v[92:95], v194, v26 op_sel_hi:[0,0,0] cbsz:2 blgp:2
	v_mfma_scale_f32_16x16x128_f8f6f4 v[80:83], v[142:147], v[8:13], v[80:83], v190, v184 op_sel_hi:[0,0,0] cbsz:2 blgp:2
	v_mfma_scale_f32_16x16x128_f8f6f4 v[76:79], v[148:153], v[8:13], v[76:79], v194, v184 op_sel_hi:[0,0,0] cbsz:2 blgp:2
	s_add_i32 s50, 0, 0x18000
	s_add_i32 s51, 0, 0x1c000
	v_add_u32_e32 v252, 0x18000, v1
	v_add_u32_e32 v253, 0x1c000, v1
	v_lshl_add_u64 v[248:249], v[234:235], 0, s[8:9]
	v_lshl_add_u64 v[250:251], v[234:235], 0, s[10:11]
	v_mfma_scale_f32_16x16x128_f8f6f4 v[68:71], v[142:147], v[14:19], v[68:71], v190, v188 op_sel_hi:[0,0,0] cbsz:2 blgp:2
	v_mfma_scale_f32_16x16x128_f8f6f4 v[56:59], v[148:153], v[14:19], v[56:59], v194, v188 op_sel_hi:[0,0,0] cbsz:2 blgp:2
	v_mfma_scale_f32_16x16x128_f8f6f4 v[190:193], v[142:147], v[20:25], v[52:55], v190, v214 op_sel_hi:[0,0,0] cbsz:2 blgp:2
	v_mfma_scale_f32_16x16x128_f8f6f4 v[194:197], v[148:153], v[20:25], v[44:47], v194, v214 op_sel_hi:[0,0,0] cbsz:2 blgp:2
	v_mfma_scale_f32_16x16x128_f8f6f4 v[88:91], v[154:159], v[2:7], v[88:91], v198, v26 op_sel_hi:[0,0,0] cbsz:2 blgp:2
	v_mfma_scale_f32_16x16x128_f8f6f4 v[84:87], v[160:165], v[2:7], v[84:87], v202, v26 op_sel_hi:[0,0,0] cbsz:2 blgp:2
	v_mfma_scale_f32_16x16x128_f8f6f4 v[72:75], v[154:159], v[8:13], v[72:75], v198, v184 op_sel_hi:[0,0,0] cbsz:2 blgp:2
	v_mfma_scale_f32_16x16x128_f8f6f4 v[182:185], v[160:165], v[8:13], v[64:67], v202, v184 op_sel_hi:[0,0,0] cbsz:2 blgp:2
	v_mfma_scale_f32_16x16x128_f8f6f4 v[216:219], v[154:159], v[14:19], v[60:63], v198, v188 op_sel_hi:[0,0,0] cbsz:2 blgp:2
	v_mfma_scale_f32_16x16x128_f8f6f4 v[186:189], v[160:165], v[14:19], v[48:51], v202, v188 op_sel_hi:[0,0,0] cbsz:2 blgp:2
	v_mfma_scale_f32_16x16x128_f8f6f4 v[198:201], v[154:159], v[20:25], v[40:43], v198, v214 op_sel_hi:[0,0,0] cbsz:2 blgp:2
	v_mfma_scale_f32_16x16x128_f8f6f4 v[212:215], v[160:165], v[20:25], v[36:39], v202, v214 op_sel_hi:[0,0,0] cbsz:2 blgp:2
	s_barrier
	s_mov_b32 m0, s41
	ds_read_b128 v[36:39], v252
	ds_read_b128 v[52:55], v252 offset:1024
	ds_read_b128 v[42:45], v252 offset:2048
	ds_read_b128 v[64:67], v252 offset:3072
	ds_read_b128 v[142:145], v253
	ds_read_b128 v[224:227], v253 offset:1024
	ds_read_b128 v[148:151], v253 offset:2048
	ds_read_b128 v[228:231], v253 offset:3072
	ds_read_b128 v[6:9], v140 offset:32768
	ds_read_b128 v[10:13], v140 offset:33792
	ds_read_b128 v[14:17], v140 offset:34816
	ds_read_b128 v[18:21], v140 offset:35840
	ds_read_b128 v[22:25], v140 offset:36864
	ds_read_b128 v[26:29], v140 offset:37888
	global_load_lds_dwordx4 v[248:249], off
	s_mov_b32 m0, s42
	ds_read_b128 v[48:51], v140 offset:38912
	ds_read_b128 v[60:63], v140 offset:39936
	global_load_lds_dwordx4 v[250:251], off
	s_waitcnt vmcnt(8)
	s_waitcnt lgkmcnt(0)
	s_barrier
	s_waitcnt lgkmcnt(0)
	v_mov_b32_e32 v40, v52
	v_mov_b32_e32 v41, v53
	v_mov_b32_e32 v46, v64
	v_mov_b32_e32 v47, v65
	v_mov_b32_e32 v52, v60
	v_mov_b32_e32 v53, v61
	v_mfma_scale_f32_16x16x128_f8f6f4 v[128:131], v[36:41], v[6:11], v[128:131], v54, v12 op_sel_hi:[0,0,0] cbsz:2 blgp:2
	v_mfma_scale_f32_16x16x128_f8f6f4 v[124:127], v[42:47], v[6:11], v[124:127], v66, v12 op_sel_hi:[0,0,0] cbsz:2 blgp:2
	v_mfma_scale_f32_16x16x128_f8f6f4 v[120:123], v[36:41], v[14:19], v[120:123], v54, v20 op_sel_hi:[0,0,0] cbsz:2 blgp:2
	v_mfma_scale_f32_16x16x128_f8f6f4 v[116:119], v[42:47], v[14:19], v[116:119], v66, v20 op_sel_hi:[0,0,0] cbsz:2 blgp:2
	s_add_i32 s100, s50, s29
	s_add_i32 s101, s51, s29
	s_add_i32 s50, s51, s29
	v_lshl_add_u64 v[240:241], v[232:233], 0, s[20:21]
	v_lshl_add_u64 v[242:243], v[232:233], 0, s[22:23]
	v_lshl_add_u64 v[244:245], v[232:233], 0, s[24:25]
	v_lshl_add_u64 v[246:247], v[232:233], 0, s[26:27]
	v_lshl_add_u64 v[248:249], v[234:235], 0, s[20:21]
	v_lshl_add_u64 v[250:251], v[234:235], 0, s[22:23]
	v_mfma_scale_f32_16x16x128_f8f6f4 v[112:115], v[36:41], v[22:27], v[112:115], v54, v28 op_sel_hi:[0,0,0] cbsz:2 blgp:2
	v_mfma_scale_f32_16x16x128_f8f6f4 v[108:111], v[42:47], v[22:27], v[108:111], v66, v28 op_sel_hi:[0,0,0] cbsz:2 blgp:2
	v_mfma_scale_f32_16x16x128_f8f6f4 v[104:107], v[36:41], v[48:53], v[104:107], v54, v62 op_sel_hi:[0,0,0] cbsz:2 blgp:2
	v_mfma_scale_f32_16x16x128_f8f6f4 v[100:103], v[42:47], v[48:53], v[100:103], v66, v62 op_sel_hi:[0,0,0] cbsz:2 blgp:2
	v_mov_b32_e32 v146, v224
	v_mov_b32_e32 v147, v225
	v_mov_b32_e32 v152, v228
	v_mov_b32_e32 v153, v229
	v_mfma_scale_f32_16x16x128_f8f6f4 v[2:5], v[142:147], v[6:11], v[220:223], v226, v12 op_sel_hi:[0,0,0] cbsz:2 blgp:2
	s_nop 0
	v_mfma_scale_f32_16x16x128_f8f6f4 v[6:9], v[148:153], v[6:11], v[166:169], v230, v12 op_sel_hi:[0,0,0] cbsz:2 blgp:2
	v_mfma_scale_f32_16x16x128_f8f6f4 v[10:13], v[142:147], v[14:19], v[204:207], v226, v20 op_sel_hi:[0,0,0] cbsz:2 blgp:2
	v_mfma_scale_f32_16x16x128_f8f6f4 v[14:17], v[148:153], v[14:19], v[170:173], v230, v20 op_sel_hi:[0,0,0] cbsz:2 blgp:2
	v_mfma_scale_f32_16x16x128_f8f6f4 v[18:21], v[142:147], v[22:27], v[174:177], v226, v28 op_sel_hi:[0,0,0] cbsz:2 blgp:2
	v_mfma_scale_f32_16x16x128_f8f6f4 v[22:25], v[148:153], v[22:27], v[178:181], v230, v28 op_sel_hi:[0,0,0] cbsz:2 blgp:2
	v_mfma_scale_f32_16x16x128_f8f6f4 v[26:29], v[142:147], v[48:53], v[208:211], v226, v62 op_sel_hi:[0,0,0] cbsz:2 blgp:2
	v_mfma_scale_f32_16x16x128_f8f6f4 v[30:33], v[148:153], v[48:53], v[30:33], v230, v62 op_sel_hi:[0,0,0] cbsz:2 blgp:2
	s_barrier
	s_mov_b32 m0, s100
	ds_read_b128 v[60:63], v140 offset:49152
	ds_read_b128 v[48:51], v140 offset:50176
	ds_read_b128 v[154:157], v140 offset:51200
	global_load_lds_dwordx4 v[240:241], off
	s_add_i32 m0, s100, 0x2000
	ds_read_b128 v[170:173], v140 offset:52224
	global_load_lds_dwordx4 v[242:243], off
	s_mov_b32 m0, s101
	ds_read_b128 v[160:163], v140 offset:53248
	global_load_lds_dwordx4 v[244:245], off
	s_add_i32 m0, s101, 0x2000
	ds_read_b128 v[174:177], v140 offset:54272
	global_load_lds_dwordx4 v[246:247], off
	s_mov_b32 m0, s43
	ds_read_b128 v[166:169], v140 offset:55296
	global_load_lds_dwordx4 v[248:249], off
	s_mov_b32 m0, s54
	ds_read_b128 v[178:181], v140 offset:56320
	global_load_lds_dwordx4 v[250:251], off
	s_waitcnt vmcnt(8)
	s_waitcnt lgkmcnt(0)
	s_barrier
	s_waitcnt lgkmcnt(0)
	v_mov_b32_e32 v64, v48
	v_mov_b32_e32 v65, v49
	v_mov_b32_e32 v158, v170
	v_mov_b32_e32 v159, v171
	v_mov_b32_e32 v164, v174
	v_mov_b32_e32 v165, v175
	v_mov_b32_e32 v170, v178
	v_mov_b32_e32 v171, v179
	v_mfma_scale_f32_16x16x128_f8f6f4 v[96:99], v[36:41], v[60:65], v[96:99], v54, v50 op_sel_hi:[0,0,0] cbsz:2 blgp:2
	v_mfma_scale_f32_16x16x128_f8f6f4 v[92:95], v[42:47], v[60:65], v[92:95], v66, v50 op_sel_hi:[0,0,0] cbsz:2 blgp:2
	v_mfma_scale_f32_16x16x128_f8f6f4 v[80:83], v[36:41], v[154:159], v[80:83], v54, v172 op_sel_hi:[0,0,0] cbsz:2 blgp:2
	v_mfma_scale_f32_16x16x128_f8f6f4 v[76:79], v[42:47], v[154:159], v[76:79], v66, v172 op_sel_hi:[0,0,0] cbsz:2 blgp:2
	s_add_i32 s76, s76, 2
	s_add_u32 s48, s48, 0x100
	s_addc_u32 s49, s49, 0
	s_add_u32 s66, s66, 0x100
	s_addc_u32 s67, s67, 0
	v_mfma_scale_f32_16x16x128_f8f6f4 v[68:71], v[36:41], v[160:165], v[68:71], v54, v176 op_sel_hi:[0,0,0] cbsz:2 blgp:2
	v_mfma_scale_f32_16x16x128_f8f6f4 v[56:59], v[42:47], v[160:165], v[56:59], v66, v176 op_sel_hi:[0,0,0] cbsz:2 blgp:2
	v_mfma_scale_f32_16x16x128_f8f6f4 v[52:55], v[36:41], v[166:171], v[190:193], v54, v180 op_sel_hi:[0,0,0] cbsz:2 blgp:2
	v_mfma_scale_f32_16x16x128_f8f6f4 v[44:47], v[42:47], v[166:171], v[194:197], v66, v180 op_sel_hi:[0,0,0] cbsz:2 blgp:2
	v_mfma_scale_f32_16x16x128_f8f6f4 v[88:91], v[142:147], v[60:65], v[88:91], v226, v50 op_sel_hi:[0,0,0] cbsz:2 blgp:2
	v_mfma_scale_f32_16x16x128_f8f6f4 v[84:87], v[148:153], v[60:65], v[84:87], v230, v50 op_sel_hi:[0,0,0] cbsz:2 blgp:2
	v_mfma_scale_f32_16x16x128_f8f6f4 v[72:75], v[142:147], v[154:159], v[72:75], v226, v172 op_sel_hi:[0,0,0] cbsz:2 blgp:2
	v_mfma_scale_f32_16x16x128_f8f6f4 v[64:67], v[148:153], v[154:159], v[182:185], v230, v172 op_sel_hi:[0,0,0] cbsz:2 blgp:2
	v_mfma_scale_f32_16x16x128_f8f6f4 v[60:63], v[142:147], v[160:165], v[216:219], v226, v176 op_sel_hi:[0,0,0] cbsz:2 blgp:2
	v_mfma_scale_f32_16x16x128_f8f6f4 v[48:51], v[148:153], v[160:165], v[186:189], v230, v176 op_sel_hi:[0,0,0] cbsz:2 blgp:2
	v_mfma_scale_f32_16x16x128_f8f6f4 v[40:43], v[142:147], v[166:171], v[198:201], v226, v180 op_sel_hi:[0,0,0] cbsz:2 blgp:2
	v_mfma_scale_f32_16x16x128_f8f6f4 v[36:39], v[148:153], v[166:171], v[212:215], v230, v180 op_sel_hi:[0,0,0] cbsz:2 blgp:2
	s_barrier
	s_cmp_gt_u32 s76, 13
	s_cbranch_scc0 .LBB0_2187
	s_setprio 0
	s_and_b64 vcc, exec, s[30:31]
	s_cbranch_vccz .LBB0_2190
	s_barrier

.LBB0_2290:
	s_add_i32 s4, s66, -2
	s_add_u32 s44, s44, 0xe0080
	s_addc_u32 s45, s45, 0
	s_add_u32 s5, s46, 0x100
	v_mov_b32_e32 v2, 0
	s_addc_u32 s67, s47, 0
	s_mov_b32 s46, 0
	v_mov_b32_e32 v3, v2
	v_mov_b32_e32 v4, v2
	v_mov_b32_e32 v5, v2
	v_mov_b32_e32 v6, v2
	v_mov_b32_e32 v7, v2
	v_mov_b32_e32 v8, v2
	v_mov_b32_e32 v9, v2
	v_mov_b32_e32 v18, v2
	v_mov_b32_e32 v19, v2
	v_mov_b32_e32 v20, v2
	v_mov_b32_e32 v21, v2
	v_mov_b32_e32 v22, v2
	v_mov_b32_e32 v23, v2
	v_mov_b32_e32 v24, v2
	v_mov_b32_e32 v25, v2
	v_mov_b32_e32 v34, v2
	v_mov_b32_e32 v35, v2
	v_mov_b32_e32 v36, v2
	v_mov_b32_e32 v37, v2
	v_mov_b32_e32 v38, v2
	v_mov_b32_e32 v39, v2
	v_mov_b32_e32 v40, v2
	v_mov_b32_e32 v41, v2
	v_mov_b32_e32 v50, v2
	v_mov_b32_e32 v51, v2
	v_mov_b32_e32 v52, v2
	v_mov_b32_e32 v53, v2
	v_mov_b32_e32 v54, v2
	v_mov_b32_e32 v55, v2
	v_mov_b32_e32 v56, v2
	v_mov_b32_e32 v57, v2
	v_mov_b32_e32 v10, v2
	v_mov_b32_e32 v11, v2
	v_mov_b32_e32 v12, v2
	v_mov_b32_e32 v13, v2
	v_mov_b32_e32 v14, v2
	v_mov_b32_e32 v15, v2
	v_mov_b32_e32 v16, v2
	v_mov_b32_e32 v17, v2
	v_mov_b32_e32 v26, v2
	v_mov_b32_e32 v27, v2
	v_mov_b32_e32 v28, v2
	v_mov_b32_e32 v29, v2
	v_mov_b32_e32 v30, v2
	v_mov_b32_e32 v31, v2
	v_mov_b32_e32 v32, v2
	v_mov_b32_e32 v33, v2
	v_mov_b32_e32 v42, v2
	v_mov_b32_e32 v43, v2
	v_mov_b32_e32 v44, v2
	v_mov_b32_e32 v45, v2
	v_mov_b32_e32 v46, v2
	v_mov_b32_e32 v47, v2
	v_mov_b32_e32 v48, v2
	v_mov_b32_e32 v49, v2
	v_mov_b32_e32 v58, v2
	v_mov_b32_e32 v59, v2
	v_mov_b32_e32 v60, v2
	v_mov_b32_e32 v61, v2
	v_mov_b32_e32 v62, v2
	v_mov_b32_e32 v63, v2
	v_mov_b32_e32 v64, v2
	v_mov_b32_e32 v65, v2
	v_mov_b32_e32 v66, v2
	v_mov_b32_e32 v67, v2
	v_mov_b32_e32 v68, v2
	v_mov_b32_e32 v69, v2
	v_mov_b32_e32 v70, v2
	v_mov_b32_e32 v71, v2
	v_mov_b32_e32 v72, v2
	v_mov_b32_e32 v73, v2
	v_mov_b32_e32 v82, v2
	v_mov_b32_e32 v83, v2
	v_mov_b32_e32 v84, v2
	v_mov_b32_e32 v85, v2
	v_mov_b32_e32 v86, v2
	v_mov_b32_e32 v87, v2
	v_mov_b32_e32 v88, v2
	v_mov_b32_e32 v89, v2
	v_mov_b32_e32 v98, v2
	v_mov_b32_e32 v99, v2
	v_mov_b32_e32 v100, v2
	v_mov_b32_e32 v101, v2
	v_mov_b32_e32 v102, v2
	v_mov_b32_e32 v103, v2
	v_mov_b32_e32 v104, v2
	v_mov_b32_e32 v105, v2
	v_mov_b32_e32 v114, v2
	v_mov_b32_e32 v115, v2
	v_mov_b32_e32 v116, v2
	v_mov_b32_e32 v117, v2
	v_mov_b32_e32 v118, v2
	v_mov_b32_e32 v119, v2
	v_mov_b32_e32 v120, v2
	v_mov_b32_e32 v121, v2
	v_mov_b32_e32 v74, v2
	v_mov_b32_e32 v75, v2
	v_mov_b32_e32 v76, v2
	v_mov_b32_e32 v77, v2
	v_mov_b32_e32 v78, v2
	v_mov_b32_e32 v79, v2
	v_mov_b32_e32 v80, v2
	v_mov_b32_e32 v81, v2
	v_mov_b32_e32 v90, v2
	v_mov_b32_e32 v91, v2
	v_mov_b32_e32 v92, v2
	v_mov_b32_e32 v93, v2
	v_mov_b32_e32 v94, v2
	v_mov_b32_e32 v95, v2
	v_mov_b32_e32 v96, v2
	v_mov_b32_e32 v97, v2
	v_mov_b32_e32 v106, v2
	v_mov_b32_e32 v107, v2
	v_mov_b32_e32 v108, v2
	v_mov_b32_e32 v109, v2
	v_mov_b32_e32 v110, v2
	v_mov_b32_e32 v111, v2
	v_mov_b32_e32 v112, v2
	v_mov_b32_e32 v113, v2
	v_mov_b32_e32 v122, v2
	v_mov_b32_e32 v123, v2
	v_mov_b32_e32 v124, v2
	v_mov_b32_e32 v125, v2
	v_mov_b32_e32 v126, v2
	v_mov_b32_e32 v127, v2
	v_mov_b32_e32 v128, v2
	v_mov_b32_e32 v129, v2
	v_readfirstlane_b32 s100, v0
	s_bitcmp1_b32 s100, 8
	s_cbranch_scc0 .Lfp6_prio_skip3
	s_setprio 1
.Lfp6_prio_skip3:
.LBB0_2291:
	ds_read_b128 v[144:147], v140
	ds_read_b128 v[190:193], v140 offset:1024
	ds_read_b128 v[150:153], v140 offset:2048
	ds_read_b128 v[194:197], v140 offset:3072
	ds_read_b128 v[156:159], v141
	ds_read_b128 v[198:201], v141 offset:1024
	ds_read_b128 v[162:165], v141 offset:2048
	ds_read_b128 v[202:205], v141 offset:3072
	v_lshl_add_u64 v[138:139], s[44:45], 0, v[136:137]
	s_add_i32 m0, s33, 0xc000
	ds_read_b128 v[168:171], v142
	ds_read_b128 v[206:209], v142 offset:1024
	ds_read_b128 v[174:177], v142 offset:2048
	ds_read_b128 v[210:213], v142 offset:3072
	ds_read_b128 v[180:183], v142 offset:4096
	ds_read_b128 v[214:217], v142 offset:5120
	ds_read_b128 v[186:189], v142 offset:6144
	ds_read_b128 v[218:221], v142 offset:7168
	global_load_lds_dwordx4 v[138:139], off
	s_add_i32 m0, s33, 0xe000
	v_lshl_add_u64 v[138:139], v[138:139], 0, s[8:9]
	global_load_lds_dwordx4 v[138:139], off
	s_waitcnt vmcnt(8)
	s_waitcnt lgkmcnt(0)
	s_barrier
	s_waitcnt lgkmcnt(0)
	v_mov_b32_e32 v148, v190
	v_mov_b32_e32 v149, v191
	v_mov_b32_e32 v154, v194
	v_mov_b32_e32 v155, v195
	v_mov_b32_e32 v172, v206
	v_mov_b32_e32 v173, v207
	v_mov_b32_e32 v178, v210
	v_mov_b32_e32 v179, v211
	v_mov_b32_e32 v184, v214
	v_mov_b32_e32 v185, v215
	v_mfma_scale_f32_16x16x128_f8f6f4 v[126:129], v[144:149], v[168:173], v[126:129], v192, v208 op_sel_hi:[0,0,0] cbsz:2 blgp:2
	v_mov_b32_e32 v190, v218
	v_mov_b32_e32 v191, v219
	v_mfma_scale_f32_16x16x128_f8f6f4 v[122:125], v[150:155], v[168:173], v[122:125], v196, v208 op_sel_hi:[0,0,0] cbsz:2 blgp:2
	v_mfma_scale_f32_16x16x128_f8f6f4 v[110:113], v[144:149], v[174:179], v[110:113], v192, v212 op_sel_hi:[0,0,0] cbsz:2 blgp:2
	v_mfma_scale_f32_16x16x128_f8f6f4 v[106:109], v[150:155], v[174:179], v[106:109], v196, v212 op_sel_hi:[0,0,0] cbsz:2 blgp:2
	s_add_i32 s76, s46, 2
	s_add_u32 s48, s44, 0xfff20080
	s_addc_u32 s47, s45, -1
	s_cmp_eq_u32 s4, s46
	s_cselect_b32 s46, s38, s48
	s_cselect_b32 s47, s39, s47
	s_cselect_b32 s49, s7, s67
	s_cselect_b32 s48, s6, s5
	s_add_i32 s100, s58, s29
	s_add_i32 s101, s59, s29
	v_lshl_add_u64 v[138:139], s[48:49], 0, v[132:133]
	v_lshl_add_u64 v[246:247], s[46:47], 0, v[130:131]
	v_lshl_add_u64 v[248:249], v[138:139], 0, s[8:9]
	v_lshl_add_u64 v[250:251], v[138:139], 0, s[10:11]
	v_lshl_add_u64 v[252:253], v[138:139], 0, s[12:13]
	v_mfma_scale_f32_16x16x128_f8f6f4 v[94:97], v[144:149], v[180:185], v[94:97], v192, v216 op_sel_hi:[0,0,0] cbsz:2 blgp:2
	v_mfma_scale_f32_16x16x128_f8f6f4 v[90:93], v[150:155], v[180:185], v[90:93], v196, v216 op_sel_hi:[0,0,0] cbsz:2 blgp:2
	v_mfma_scale_f32_16x16x128_f8f6f4 v[222:225], v[144:149], v[186:191], v[78:81], v192, v220 op_sel_hi:[0,0,0] cbsz:2 blgp:2
	v_mfma_scale_f32_16x16x128_f8f6f4 v[226:229], v[150:155], v[186:191], v[74:77], v196, v220 op_sel_hi:[0,0,0] cbsz:2 blgp:2
	v_mov_b32_e32 v160, v198
	v_mov_b32_e32 v161, v199
	v_mov_b32_e32 v166, v202
	v_mov_b32_e32 v167, v203
	v_mfma_scale_f32_16x16x128_f8f6f4 v[118:121], v[156:161], v[168:173], v[118:121], v200, v208 op_sel_hi:[0,0,0] cbsz:2 blgp:2
	s_nop 0
	v_mfma_scale_f32_16x16x128_f8f6f4 v[114:117], v[162:167], v[168:173], v[114:117], v204, v208 op_sel_hi:[0,0,0] cbsz:2 blgp:2
	v_mfma_scale_f32_16x16x128_f8f6f4 v[102:105], v[156:161], v[174:179], v[102:105], v200, v212 op_sel_hi:[0,0,0] cbsz:2 blgp:2
	v_mfma_scale_f32_16x16x128_f8f6f4 v[98:101], v[162:167], v[174:179], v[98:101], v204, v212 op_sel_hi:[0,0,0] cbsz:2 blgp:2
	v_mfma_scale_f32_16x16x128_f8f6f4 v[168:171], v[156:161], v[180:185], v[86:89], v200, v216 op_sel_hi:[0,0,0] cbsz:2 blgp:2
	v_mfma_scale_f32_16x16x128_f8f6f4 v[172:175], v[162:167], v[180:185], v[82:85], v204, v216 op_sel_hi:[0,0,0] cbsz:2 blgp:2
	v_mfma_scale_f32_16x16x128_f8f6f4 v[176:179], v[156:161], v[186:191], v[70:73], v200, v220 op_sel_hi:[0,0,0] cbsz:2 blgp:2
	v_mfma_scale_f32_16x16x128_f8f6f4 v[180:183], v[162:167], v[186:191], v[66:69], v204, v220 op_sel_hi:[0,0,0] cbsz:2 blgp:2
	s_barrier
	s_mov_b32 m0, s100
	ds_read_b128 v[66:69], v142 offset:16384
	ds_read_b128 v[184:187], v142 offset:17408
	ds_read_b128 v[72:75], v142 offset:18432
	global_load_lds_dwordx4 v[138:139], off
	s_add_i32 m0, s100, 0x2000
	ds_read_b128 v[188:191], v142 offset:19456
	global_load_lds_dwordx4 v[248:249], off
	s_mov_b32 m0, s101
	ds_read_b128 v[78:81], v142 offset:20480
	global_load_lds_dwordx4 v[250:251], off
	s_add_i32 m0, s101, 0x2000
	ds_read_b128 v[206:209], v142 offset:21504
	global_load_lds_dwordx4 v[252:253], off
	s_mov_b32 m0, s33
	ds_read_b128 v[84:87], v142 offset:22528
	global_load_lds_dwordx4 v[246:247], off
	s_mov_b32 m0, s40
	v_lshl_add_u64 v[70:71], v[246:247], 0, s[8:9]
	ds_read_b128 v[210:213], v142 offset:23552
	global_load_lds_dwordx4 v[70:71], off
	s_waitcnt vmcnt(8)
	s_waitcnt lgkmcnt(0)
	s_barrier
	s_waitcnt lgkmcnt(0)
	v_mov_b32_e32 v70, v184
	v_mov_b32_e32 v71, v185
	v_mov_b32_e32 v76, v188
	v_mov_b32_e32 v77, v189
	v_mfma_scale_f32_16x16x128_f8f6f4 v[62:65], v[144:149], v[66:71], v[62:65], v192, v186 op_sel_hi:[0,0,0] cbsz:2 blgp:2
	v_mov_b32_e32 v82, v206
	v_mov_b32_e32 v83, v207
	v_mov_b32_e32 v88, v210
	v_mfma_scale_f32_16x16x128_f8f6f4 v[58:61], v[150:155], v[66:71], v[58:61], v196, v186 op_sel_hi:[0,0,0] cbsz:2 blgp:2
	v_mov_b32_e32 v89, v211
	v_mfma_scale_f32_16x16x128_f8f6f4 v[46:49], v[144:149], v[72:77], v[46:49], v192, v190 op_sel_hi:[0,0,0] cbsz:2 blgp:2
	v_mfma_scale_f32_16x16x128_f8f6f4 v[42:45], v[150:155], v[72:77], v[42:45], v196, v190 op_sel_hi:[0,0,0] cbsz:2 blgp:2
	s_add_i32 s46, 0, 0x18000
	s_add_i32 s47, 0, 0x1c000
	v_add_u32_e32 v143, 0x18000, v1
	v_add_u32_e32 v134, 0x1c000, v1
	v_lshl_add_u64 v[248:249], v[246:247], 0, s[10:11]
	v_lshl_add_u64 v[250:251], v[246:247], 0, s[12:13]
	v_mfma_scale_f32_16x16x128_f8f6f4 v[214:217], v[144:149], v[78:83], v[30:33], v192, v208 op_sel_hi:[0,0,0] cbsz:2 blgp:2
	v_mfma_scale_f32_16x16x128_f8f6f4 v[218:221], v[150:155], v[78:83], v[26:29], v196, v208 op_sel_hi:[0,0,0] cbsz:2 blgp:2
	v_mfma_scale_f32_16x16x128_f8f6f4 v[192:195], v[144:149], v[84:89], v[14:17], v192, v212 op_sel_hi:[0,0,0] cbsz:2 blgp:2
	v_mfma_scale_f32_16x16x128_f8f6f4 v[196:199], v[150:155], v[84:89], v[10:13], v196, v212 op_sel_hi:[0,0,0] cbsz:2 blgp:2
	v_mfma_scale_f32_16x16x128_f8f6f4 v[54:57], v[156:161], v[66:71], v[54:57], v200, v186 op_sel_hi:[0,0,0] cbsz:2 blgp:2
	v_mfma_scale_f32_16x16x128_f8f6f4 v[50:53], v[162:167], v[66:71], v[50:53], v204, v186 op_sel_hi:[0,0,0] cbsz:2 blgp:2
	v_mfma_scale_f32_16x16x128_f8f6f4 v[38:41], v[156:161], v[72:77], v[38:41], v200, v190 op_sel_hi:[0,0,0] cbsz:2 blgp:2
	v_mfma_scale_f32_16x16x128_f8f6f4 v[184:187], v[162:167], v[72:77], v[34:37], v204, v190 op_sel_hi:[0,0,0] cbsz:2 blgp:2
	v_mfma_scale_f32_16x16x128_f8f6f4 v[188:191], v[156:161], v[78:83], v[22:25], v200, v208 op_sel_hi:[0,0,0] cbsz:2 blgp:2
	v_mfma_scale_f32_16x16x128_f8f6f4 v[206:209], v[162:167], v[78:83], v[18:21], v204, v208 op_sel_hi:[0,0,0] cbsz:2 blgp:2
	v_mfma_scale_f32_16x16x128_f8f6f4 v[200:203], v[156:161], v[84:89], v[6:9], v200, v212 op_sel_hi:[0,0,0] cbsz:2 blgp:2
	v_mfma_scale_f32_16x16x128_f8f6f4 v[210:213], v[162:167], v[84:89], v[2:5], v204, v212 op_sel_hi:[0,0,0] cbsz:2 blgp:2
	s_barrier
	s_mov_b32 m0, s41
	ds_read_b128 v[2:5], v143
	ds_read_b128 v[230:233], v143 offset:1024
	ds_read_b128 v[8:11], v143 offset:2048
	ds_read_b128 v[234:237], v143 offset:3072
	ds_read_b128 v[144:147], v134
	ds_read_b128 v[238:241], v134 offset:1024
	ds_read_b128 v[150:153], v134 offset:2048
	ds_read_b128 v[242:245], v134 offset:3072
	ds_read_b128 v[14:17], v142 offset:32768
	ds_read_b128 v[66:69], v142 offset:33792
	ds_read_b128 v[20:23], v142 offset:34816
	ds_read_b128 v[70:73], v142 offset:35840
	ds_read_b128 v[26:29], v142 offset:36864
	ds_read_b128 v[80:83], v142 offset:37888
	global_load_lds_dwordx4 v[248:249], off
	s_mov_b32 m0, s42
	ds_read_b128 v[32:35], v142 offset:38912
	ds_read_b128 v[154:157], v142 offset:39936
	global_load_lds_dwordx4 v[250:251], off
	s_waitcnt vmcnt(8)
	s_waitcnt lgkmcnt(0)
	s_barrier
	s_waitcnt lgkmcnt(0)
	v_mov_b32_e32 v6, v230
	v_mov_b32_e32 v7, v231
	v_mov_b32_e32 v12, v234
	v_mov_b32_e32 v13, v235
	v_mov_b32_e32 v18, v66
	v_mov_b32_e32 v19, v67
	v_mov_b32_e32 v24, v70
	v_mov_b32_e32 v25, v71
	v_mov_b32_e32 v30, v80
	v_mov_b32_e32 v31, v81
	v_mov_b32_e32 v36, v154
	v_mov_b32_e32 v37, v155
	v_mfma_scale_f32_16x16x128_f8f6f4 v[126:129], v[2:7], v[14:19], v[126:129], v232, v68 op_sel_hi:[0,0,0] cbsz:2 blgp:2
	v_mfma_scale_f32_16x16x128_f8f6f4 v[122:125], v[8:13], v[14:19], v[122:125], v236, v68 op_sel_hi:[0,0,0] cbsz:2 blgp:2
	v_mfma_scale_f32_16x16x128_f8f6f4 v[110:113], v[2:7], v[20:25], v[110:113], v232, v72 op_sel_hi:[0,0,0] cbsz:2 blgp:2
	v_mfma_scale_f32_16x16x128_f8f6f4 v[106:109], v[8:13], v[20:25], v[106:109], v236, v72 op_sel_hi:[0,0,0] cbsz:2 blgp:2
	s_add_i32 s100, s46, s29
	s_add_i32 s101, s47, s29
	s_add_i32 s46, s47, s29
	v_lshl_add_u64 v[248:249], v[138:139], 0, s[24:25]
	v_lshl_add_u64 v[250:251], v[138:139], 0, s[26:27]
	v_lshl_add_u64 v[252:253], v[138:139], 0, s[30:31]
	v_mfma_scale_f32_16x16x128_f8f6f4 v[94:97], v[2:7], v[26:31], v[94:97], v232, v82 op_sel_hi:[0,0,0] cbsz:2 blgp:2
	v_mfma_scale_f32_16x16x128_f8f6f4 v[90:93], v[8:13], v[26:31], v[90:93], v236, v82 op_sel_hi:[0,0,0] cbsz:2 blgp:2
	v_mfma_scale_f32_16x16x128_f8f6f4 v[78:81], v[2:7], v[32:37], v[222:225], v232, v156 op_sel_hi:[0,0,0] cbsz:2 blgp:2
	v_mfma_scale_f32_16x16x128_f8f6f4 v[74:77], v[8:13], v[32:37], v[226:229], v236, v156 op_sel_hi:[0,0,0] cbsz:2 blgp:2
	v_mov_b32_e32 v148, v238
	v_mov_b32_e32 v149, v239
	v_mov_b32_e32 v154, v242
	v_mov_b32_e32 v155, v243
	v_mfma_scale_f32_16x16x128_f8f6f4 v[118:121], v[144:149], v[14:19], v[118:121], v240, v68 op_sel_hi:[0,0,0] cbsz:2 blgp:2
	s_nop 0
	v_mfma_scale_f32_16x16x128_f8f6f4 v[114:117], v[150:155], v[14:19], v[114:117], v244, v68 op_sel_hi:[0,0,0] cbsz:2 blgp:2
	v_mfma_scale_f32_16x16x128_f8f6f4 v[102:105], v[144:149], v[20:25], v[102:105], v240, v72 op_sel_hi:[0,0,0] cbsz:2 blgp:2
	v_mfma_scale_f32_16x16x128_f8f6f4 v[98:101], v[150:155], v[20:25], v[98:101], v244, v72 op_sel_hi:[0,0,0] cbsz:2 blgp:2
	v_mfma_scale_f32_16x16x128_f8f6f4 v[86:89], v[144:149], v[26:31], v[168:171], v240, v82 op_sel_hi:[0,0,0] cbsz:2 blgp:2
	v_mfma_scale_f32_16x16x128_f8f6f4 v[82:85], v[150:155], v[26:31], v[172:175], v244, v82 op_sel_hi:[0,0,0] cbsz:2 blgp:2
	v_mfma_scale_f32_16x16x128_f8f6f4 v[70:73], v[144:149], v[32:37], v[176:179], v240, v156 op_sel_hi:[0,0,0] cbsz:2 blgp:2
	v_mfma_scale_f32_16x16x128_f8f6f4 v[66:69], v[150:155], v[32:37], v[180:183], v244, v156 op_sel_hi:[0,0,0] cbsz:2 blgp:2
	s_barrier
	s_mov_b32 m0, s100
	ds_read_b128 v[18:21], v142 offset:49152
	ds_read_b128 v[22:25], v142 offset:50176
	ds_read_b128 v[156:159], v142 offset:51200
	global_load_lds_dwordx4 v[248:249], off
	s_add_i32 m0, s100, 0x2000
	ds_read_b128 v[32:35], v142 offset:52224
	global_load_lds_dwordx4 v[250:251], off
	s_mov_b32 m0, s101
	ds_read_b128 v[162:165], v142 offset:53248
	global_load_lds_dwordx4 v[252:253], off
	s_add_i32 m0, s101, 0x2000
	v_lshl_add_u64 v[14:15], v[138:139], 0, s[34:35]
	ds_read_b128 v[172:175], v142 offset:54272
	global_load_lds_dwordx4 v[14:15], off
	s_mov_b32 m0, s51
	v_lshl_add_u64 v[14:15], v[246:247], 0, s[24:25]
	ds_read_b128 v[168:171], v142 offset:55296
	global_load_lds_dwordx4 v[14:15], off
	s_mov_b32 m0, s52
	v_lshl_add_u64 v[14:15], v[246:247], 0, s[26:27]
	ds_read_b128 v[176:179], v142 offset:56320
	global_load_lds_dwordx4 v[14:15], off
	s_waitcnt vmcnt(8)
	s_waitcnt lgkmcnt(0)
	s_barrier
	s_waitcnt lgkmcnt(0)
	v_mov_b32_e32 v160, v32
	v_mov_b32_e32 v161, v33
	v_mov_b32_e32 v166, v172
	v_mov_b32_e32 v167, v173
	v_mov_b32_e32 v172, v176
	v_mov_b32_e32 v173, v177
	v_mfma_scale_f32_16x16x128_f8f6f4 v[62:65], v[2:7], v[18:23], v[62:65], v232, v24 op_sel_hi:[0,0,0] cbsz:2 blgp:2
	v_mfma_scale_f32_16x16x128_f8f6f4 v[58:61], v[8:13], v[18:23], v[58:61], v236, v24 op_sel_hi:[0,0,0] cbsz:2 blgp:2
	v_mfma_scale_f32_16x16x128_f8f6f4 v[46:49], v[2:7], v[156:161], v[46:49], v232, v34 op_sel_hi:[0,0,0] cbsz:2 blgp:2
	v_mfma_scale_f32_16x16x128_f8f6f4 v[42:45], v[8:13], v[156:161], v[42:45], v236, v34 op_sel_hi:[0,0,0] cbsz:2 blgp:2
	v_mfma_scale_f32_16x16x128_f8f6f4 v[30:33], v[2:7], v[162:167], v[214:217], v232, v174 op_sel_hi:[0,0,0] cbsz:2 blgp:2
	v_mfma_scale_f32_16x16x128_f8f6f4 v[26:29], v[8:13], v[162:167], v[218:221], v236, v174 op_sel_hi:[0,0,0] cbsz:2 blgp:2
	v_mfma_scale_f32_16x16x128_f8f6f4 v[14:17], v[2:7], v[168:173], v[192:195], v232, v178 op_sel_hi:[0,0,0] cbsz:2 blgp:2
	v_mfma_scale_f32_16x16x128_f8f6f4 v[10:13], v[8:13], v[168:173], v[196:199], v236, v178 op_sel_hi:[0,0,0] cbsz:2 blgp:2
	v_mfma_scale_f32_16x16x128_f8f6f4 v[54:57], v[144:149], v[18:23], v[54:57], v240, v24 op_sel_hi:[0,0,0] cbsz:2 blgp:2
	v_mfma_scale_f32_16x16x128_f8f6f4 v[50:53], v[150:155], v[18:23], v[50:53], v244, v24 op_sel_hi:[0,0,0] cbsz:2 blgp:2
	v_mfma_scale_f32_16x16x128_f8f6f4 v[38:41], v[144:149], v[156:161], v[38:41], v240, v34 op_sel_hi:[0,0,0] cbsz:2 blgp:2
	v_mfma_scale_f32_16x16x128_f8f6f4 v[34:37], v[150:155], v[156:161], v[184:187], v244, v34 op_sel_hi:[0,0,0] cbsz:2 blgp:2
	v_mfma_scale_f32_16x16x128_f8f6f4 v[22:25], v[144:149], v[162:167], v[188:191], v240, v174 op_sel_hi:[0,0,0] cbsz:2 blgp:2
	v_mfma_scale_f32_16x16x128_f8f6f4 v[18:21], v[150:155], v[162:167], v[206:209], v244, v174 op_sel_hi:[0,0,0] cbsz:2 blgp:2
	v_mfma_scale_f32_16x16x128_f8f6f4 v[6:9], v[144:149], v[168:173], v[200:203], v240, v178 op_sel_hi:[0,0,0] cbsz:2 blgp:2
	v_mfma_scale_f32_16x16x128_f8f6f4 v[2:5], v[150:155], v[168:173], v[210:213], v244, v178 op_sel_hi:[0,0,0] cbsz:2 blgp:2
	s_barrier
	s_add_u32 s44, s44, 0x100
	s_addc_u32 s45, s45, 0
	s_add_u32 s5, s5, 0x100
	s_addc_u32 s67, s67, 0
	s_cmp_ge_i32 s76, s66
	s_mov_b32 s46, s76
	s_cbranch_scc0 .LBB0_2291
	s_setprio 0
	v_readlane_b32 s76, v254, 6
	v_readlane_b32 s77, v254, 7
	v_readlane_b32 s78, v254, 8
	v_readlane_b32 s79, v254, 9
	v_readlane_b32 s80, v254, 10
	v_readlane_b32 s81, v254, 11
	v_readlane_b32 s82, v254, 12
	v_readlane_b32 s83, v254, 13
	s_and_b64 vcc, exec, s[36:37]
	s_cbranch_vccz .LBB0_2294
